# v51 + first K-iteration of non-first units: first two counted waits do not wait for the previous epilogue's stores (vmcnt 24)
# baseline (speedup 1.0000x reference)
.LBB0_303:
	s_ashr_i32 s35, s34, 31
	s_lshl_b64 s[8:9], s[34:35], 20
	s_add_u32 s36, s53, s8
	s_addc_u32 s37, s54, s9
	s_and_b64 s[8:9], s[2:3], exec
	s_cselect_b32 s35, s37, s5
	s_cselect_b32 s52, s36, s4
	s_ashr_i32 s31, s30, 31
	s_lshl_b64 s[8:9], s[30:31], 20
	s_add_u32 s38, s55, s8
	s_addc_u32 s39, s56, s9
	s_and_b64 s[8:9], s[2:3], exec
	s_cselect_b32 s31, s39, s7
	s_cselect_b32 s77, s38, s6
	s_add_u32 s4, s4, 0x80080
	s_addc_u32 s5, s5, 0
	s_add_u32 s78, s6, 0x100
	s_addc_u32 s79, s7, 0
	s_mov_b32 s80, -2
	s_waitcnt lgkmcnt(0)
	ds_read_b128 v[2:5], v234
	ds_read_b128 v[6:9], v234 offset:1024
	ds_read_b128 v[10:13], v234 offset:2048
	ds_read_b128 v[14:17], v234 offset:3072
	ds_read_b128 v[18:21], v235
	ds_read_b128 v[22:25], v235 offset:1024
	ds_read_b128 v[26:29], v235 offset:2048
	ds_read_b128 v[30:33], v235 offset:3072
	s_add_u32 s6, s4, 0xfff80080
	s_addc_u32 s7, s5, -1
	s_cmp_eq_u32 s80, 28
	s_cselect_b32 s9, s35, s7
	s_cselect_b32 s8, s52, s6
	s_cselect_b32 s7, s31, s79
	s_cselect_b32 s6, s77, s78
	v_lshl_add_u64 v[214:215], s[4:5], 0, v[206:207]
	s_add_i32 m0, s43, 0xc000
	ds_read_b128 v[98:101], v236
	ds_read_b128 v[102:105], v236 offset:1024
	ds_read_b128 v[106:109], v236 offset:2048
	ds_read_b128 v[110:113], v236 offset:3072
	ds_read_b128 v[178:181], v236 offset:4096
	ds_read_b128 v[182:185], v236 offset:5120
	ds_read_b128 v[186:189], v236 offset:6144
	ds_read_b128 v[190:193], v236 offset:7168
	global_load_lds_dwordx4 v[214:215], off
	v_lshl_add_u64 v[214:215], s[4:5], 0, v[208:209]
	s_add_i32 m0, s43, 0xe000
	s_nop 0
	global_load_lds_dwordx4 v[214:215], off
	s_waitcnt vmcnt(24)
	s_cmp_lg_u32 s18, 0
	s_cbranch_scc1 .Lrlx0_0
	s_waitcnt vmcnt(8)
.Lrlx0_0:
	s_waitcnt lgkmcnt(0)
	s_barrier
	s_waitcnt lgkmcnt(0)
	v_mfma_i32_16x16x64_i8 v[174:177], v[2:5], v[98:101], 0
	v_mfma_i32_16x16x64_i8 v[174:177], v[6:9], v[102:105], v[174:177]
	v_mfma_i32_16x16x64_i8 v[170:173], v[10:13], v[98:101], 0
	v_mfma_i32_16x16x64_i8 v[170:173], v[14:17], v[102:105], v[170:173]
	v_mfma_i32_16x16x64_i8 v[158:161], v[2:5], v[106:109], 0
	v_mfma_i32_16x16x64_i8 v[158:161], v[6:9], v[110:113], v[158:161]
	v_mfma_i32_16x16x64_i8 v[154:157], v[10:13], v[106:109], 0
	v_mfma_i32_16x16x64_i8 v[154:157], v[14:17], v[110:113], v[154:157]
	v_mfma_i32_16x16x64_i8 v[142:145], v[2:5], v[178:181], 0
	v_mfma_i32_16x16x64_i8 v[142:145], v[6:9], v[182:185], v[142:145]
	v_mfma_i32_16x16x64_i8 v[138:141], v[10:13], v[178:181], 0
	v_mfma_i32_16x16x64_i8 v[138:141], v[14:17], v[182:185], v[138:141]
	v_mfma_i32_16x16x64_i8 v[126:129], v[2:5], v[186:189], 0
	v_mfma_i32_16x16x64_i8 v[126:129], v[6:9], v[190:193], v[126:129]
	v_mfma_i32_16x16x64_i8 v[122:125], v[10:13], v[186:189], 0
	v_mfma_i32_16x16x64_i8 v[122:125], v[14:17], v[190:193], v[122:125]
	v_mfma_i32_16x16x64_i8 v[166:169], v[18:21], v[98:101], 0
	v_mfma_i32_16x16x64_i8 v[166:169], v[22:25], v[102:105], v[166:169]
	v_mfma_i32_16x16x64_i8 v[98:101], v[26:29], v[98:101], 0
	v_mfma_i32_16x16x64_i8 v[98:101], v[30:33], v[102:105], v[98:101]
	v_mfma_i32_16x16x64_i8 v[102:105], v[18:21], v[106:109], 0
	v_mfma_i32_16x16x64_i8 v[102:105], v[22:25], v[110:113], v[102:105]
	v_mfma_i32_16x16x64_i8 v[106:109], v[26:29], v[106:109], 0
	v_mfma_i32_16x16x64_i8 v[106:109], v[30:33], v[110:113], v[106:109]
	v_mfma_i32_16x16x64_i8 v[130:133], v[26:29], v[178:181], 0
	v_mfma_i32_16x16x64_i8 v[130:133], v[30:33], v[182:185], v[130:133]
	v_mfma_i32_16x16x64_i8 v[118:121], v[18:21], v[186:189], 0
	v_mfma_i32_16x16x64_i8 v[118:121], v[22:25], v[190:193], v[118:121]
	v_mfma_i32_16x16x64_i8 v[114:117], v[26:29], v[186:189], 0
	v_mfma_i32_16x16x64_i8 v[114:117], v[30:33], v[190:193], v[114:117]
	v_mfma_i32_16x16x64_i8 v[110:113], v[18:21], v[178:181], 0
	v_mfma_i32_16x16x64_i8 v[110:113], v[22:25], v[182:185], v[110:113]
	s_barrier
	s_add_i32 s81, s70, s41
	v_lshl_add_u64 v[226:227], s[6:7], 0, v[196:197]
	s_mov_b32 m0, s81
	ds_read_b128 v[134:137], v236 offset:16384
	ds_read_b128 v[146:149], v236 offset:17408
	ds_read_b128 v[150:153], v236 offset:18432
	ds_read_b128 v[162:165], v236 offset:19456
	ds_read_b128 v[178:181], v236 offset:20480
	ds_read_b128 v[182:185], v236 offset:21504
	ds_read_b128 v[186:189], v236 offset:22528
	ds_read_b128 v[190:193], v236 offset:23552
	global_load_lds_dwordx4 v[226:227], off
	s_add_i32 m0, s81, 0x2000
	s_add_u32 s82, s6, 0x80000
	v_lshl_add_u64 v[244:245], s[6:7], 0, v[198:199]
	s_addc_u32 s83, s7, 0
	s_add_i32 s81, s71, s41
	global_load_lds_dwordx4 v[244:245], off
	v_lshl_add_u64 v[214:215], s[82:83], 0, v[196:197]
	s_mov_b32 m0, s81
	v_lshl_add_u64 v[246:247], s[8:9], 0, v[196:197]
	global_load_lds_dwordx4 v[214:215], off
	v_lshl_add_u64 v[214:215], s[82:83], 0, v[198:199]
	s_add_i32 m0, s81, 0x2000
	v_lshl_add_u64 v[248:249], s[8:9], 0, v[198:199]
	global_load_lds_dwordx4 v[214:215], off
	s_mov_b32 m0, s43
	s_nop 0
	global_load_lds_dwordx4 v[246:247], off
	s_mov_b32 m0, s57
	s_nop 0
	global_load_lds_dwordx4 v[248:249], off
	s_waitcnt vmcnt(24)
	s_cmp_lg_u32 s18, 0
	s_cbranch_scc1 .Lrlx0_1
	s_waitcnt vmcnt(8)
.Lrlx0_1:
	s_waitcnt lgkmcnt(0)
	s_barrier
	s_waitcnt lgkmcnt(0)
	v_mfma_i32_16x16x64_i8 v[94:97], v[2:5], v[134:137], 0
	v_mfma_i32_16x16x64_i8 v[94:97], v[6:9], v[146:149], v[94:97]
	v_mfma_i32_16x16x64_i8 v[90:93], v[10:13], v[134:137], 0
	v_mfma_i32_16x16x64_i8 v[90:93], v[14:17], v[146:149], v[90:93]
	v_mfma_i32_16x16x64_i8 v[78:81], v[2:5], v[150:153], 0
	v_mfma_i32_16x16x64_i8 v[78:81], v[6:9], v[162:165], v[78:81]
	v_mfma_i32_16x16x64_i8 v[74:77], v[10:13], v[150:153], 0
	v_mfma_i32_16x16x64_i8 v[74:77], v[14:17], v[162:165], v[74:77]
	v_mfma_i32_16x16x64_i8 v[62:65], v[2:5], v[178:181], 0
	v_mfma_i32_16x16x64_i8 v[62:65], v[6:9], v[182:185], v[62:65]
	v_mfma_i32_16x16x64_i8 v[58:61], v[10:13], v[178:181], 0
	v_mfma_i32_16x16x64_i8 v[58:61], v[14:17], v[182:185], v[58:61]
	v_mfma_i32_16x16x64_i8 v[2:5], v[2:5], v[186:189], 0
	v_mfma_i32_16x16x64_i8 v[2:5], v[6:9], v[190:193], v[2:5]
	v_mfma_i32_16x16x64_i8 v[6:9], v[10:13], v[186:189], 0
	v_mfma_i32_16x16x64_i8 v[6:9], v[14:17], v[190:193], v[6:9]
	v_mfma_i32_16x16x64_i8 v[42:45], v[18:21], v[150:153], 0
	v_mfma_i32_16x16x64_i8 v[70:73], v[22:25], v[162:165], v[42:45]
	v_mfma_i32_16x16x64_i8 v[42:45], v[26:29], v[150:153], 0
	v_mfma_i32_16x16x64_i8 v[66:69], v[30:33], v[162:165], v[42:45]
	v_mfma_i32_16x16x64_i8 v[42:45], v[18:21], v[178:181], 0
	v_mfma_i32_16x16x64_i8 v[54:57], v[22:25], v[182:185], v[42:45]
	v_mfma_i32_16x16x64_i8 v[10:13], v[18:21], v[134:137], 0
	v_mfma_i32_16x16x64_i8 v[10:13], v[22:25], v[146:149], v[10:13]
	v_mfma_i32_16x16x64_i8 v[42:45], v[26:29], v[178:181], 0
	v_mfma_i32_16x16x64_i8 v[50:53], v[30:33], v[182:185], v[42:45]
	v_mfma_i32_16x16x64_i8 v[18:21], v[18:21], v[186:189], 0
	v_mfma_i32_16x16x64_i8 v[18:21], v[22:25], v[190:193], v[18:21]
	v_mfma_i32_16x16x64_i8 v[14:17], v[26:29], v[134:137], 0
	v_mfma_i32_16x16x64_i8 v[14:17], v[30:33], v[146:149], v[14:17]
	v_mfma_i32_16x16x64_i8 v[22:25], v[26:29], v[186:189], 0
	v_mfma_i32_16x16x64_i8 v[22:25], v[30:33], v[190:193], v[22:25]
	s_barrier
	s_add_i32 s81, 0, 0x18000
	s_add_i32 s82, 0, 0x1c000
	v_add_u32_e32 v38, s81, v229
	v_add_u32_e32 v42, s82, v229
	ds_read_b128 v[26:29], v38
	ds_read_b128 v[30:33], v38 offset:1024
	ds_read_b128 v[34:37], v38 offset:2048
	ds_read_b128 v[38:41], v38 offset:3072
	ds_read_b128 v[178:181], v42
	ds_read_b128 v[182:185], v42 offset:1024
	ds_read_b128 v[186:189], v42 offset:2048
	ds_read_b128 v[190:193], v42 offset:3072
	s_add_u32 s8, s8, 0x80000
	s_addc_u32 s9, s9, 0
	s_mov_b32 m0, s60
	v_lshl_add_u64 v[134:135], s[8:9], 0, v[196:197]
	ds_read_b128 v[42:45], v236 offset:32768
	ds_read_b128 v[46:49], v236 offset:33792
	ds_read_b128 v[82:85], v236 offset:34816
	ds_read_b128 v[86:89], v236 offset:35840
	ds_read_b128 v[214:217], v236 offset:36864
	ds_read_b128 v[218:221], v236 offset:37888
	ds_read_b128 v[222:225], v236 offset:38912
	ds_read_b128 v[240:243], v236 offset:39936
	global_load_lds_dwordx4 v[134:135], off
	v_lshl_add_u64 v[134:135], s[8:9], 0, v[198:199]
	s_mov_b32 m0, s61
	s_nop 0
	global_load_lds_dwordx4 v[134:135], off
	s_waitcnt vmcnt(8)
	s_waitcnt lgkmcnt(0)
	s_barrier
	s_waitcnt lgkmcnt(0)
	v_mfma_i32_16x16x64_i8 v[134:137], v[26:29], v[42:45], v[174:177]
	v_mfma_i32_16x16x64_i8 v[174:177], v[30:33], v[46:49], v[134:137]
	v_mfma_i32_16x16x64_i8 v[134:137], v[34:37], v[42:45], v[170:173]
	v_mfma_i32_16x16x64_i8 v[170:173], v[38:41], v[46:49], v[134:137]
	v_mfma_i32_16x16x64_i8 v[134:137], v[26:29], v[82:85], v[158:161]
	v_mfma_i32_16x16x64_i8 v[158:161], v[30:33], v[86:89], v[134:137]
	v_mfma_i32_16x16x64_i8 v[134:137], v[34:37], v[82:85], v[154:157]
	v_mfma_i32_16x16x64_i8 v[154:157], v[38:41], v[86:89], v[134:137]
	v_mfma_i32_16x16x64_i8 v[134:137], v[26:29], v[214:217], v[142:145]
	v_mfma_i32_16x16x64_i8 v[142:145], v[30:33], v[218:221], v[134:137]
	v_mfma_i32_16x16x64_i8 v[134:137], v[34:37], v[214:217], v[138:141]
	v_mfma_i32_16x16x64_i8 v[138:141], v[38:41], v[218:221], v[134:137]
	v_mfma_i32_16x16x64_i8 v[126:129], v[26:29], v[222:225], v[126:129]
	v_mfma_i32_16x16x64_i8 v[126:129], v[30:33], v[240:243], v[126:129]
	v_mfma_i32_16x16x64_i8 v[122:125], v[34:37], v[222:225], v[122:125]
	v_mfma_i32_16x16x64_i8 v[122:125], v[38:41], v[240:243], v[122:125]
	v_mfma_i32_16x16x64_i8 v[134:137], v[178:181], v[42:45], v[166:169]
	v_mfma_i32_16x16x64_i8 v[166:169], v[182:185], v[46:49], v[134:137]
	v_mfma_i32_16x16x64_i8 v[42:45], v[186:189], v[42:45], v[98:101]
	v_mfma_i32_16x16x64_i8 v[162:165], v[190:193], v[46:49], v[42:45]
	v_mfma_i32_16x16x64_i8 v[42:45], v[178:181], v[82:85], v[102:105]
	v_mfma_i32_16x16x64_i8 v[150:153], v[182:185], v[86:89], v[42:45]
	v_mfma_i32_16x16x64_i8 v[42:45], v[186:189], v[82:85], v[106:109]
	v_mfma_i32_16x16x64_i8 v[146:149], v[190:193], v[86:89], v[42:45]
	v_mfma_i32_16x16x64_i8 v[42:45], v[178:181], v[214:217], v[110:113]
	v_mfma_i32_16x16x64_i8 v[134:137], v[182:185], v[218:221], v[42:45]
	v_mfma_i32_16x16x64_i8 v[42:45], v[186:189], v[214:217], v[130:133]
	v_mfma_i32_16x16x64_i8 v[130:133], v[190:193], v[218:221], v[42:45]
	v_mfma_i32_16x16x64_i8 v[42:45], v[178:181], v[222:225], v[118:121]
	v_mfma_i32_16x16x64_i8 v[118:121], v[182:185], v[240:243], v[42:45]
	v_mfma_i32_16x16x64_i8 v[42:45], v[186:189], v[222:225], v[114:117]
	v_mfma_i32_16x16x64_i8 v[114:117], v[190:193], v[240:243], v[42:45]
	s_barrier
	s_add_i32 s8, s81, s41
	s_nop 3
	v_lshl_add_u64 v[42:43], v[226:227], 0, s[24:25]
	s_mov_b32 m0, s8
	ds_read_b128 v[82:85], v236 offset:49152
	ds_read_b128 v[98:101], v236 offset:50176
	ds_read_b128 v[102:105], v236 offset:51200
	ds_read_b128 v[106:109], v236 offset:52224
	ds_read_b128 v[110:113], v236 offset:53248
	ds_read_b128 v[214:217], v236 offset:54272
	ds_read_b128 v[218:221], v236 offset:55296
	ds_read_b128 v[222:225], v236 offset:56320
	global_load_lds_dwordx4 v[42:43], off
	s_add_i32 m0, s8, 0x2000
	s_add_u32 s6, s6, 0x80080
	v_lshl_add_u64 v[42:43], v[244:245], 0, s[24:25]
	s_addc_u32 s7, s7, 0
	s_add_i32 s8, s82, s41
	global_load_lds_dwordx4 v[42:43], off
	v_lshl_add_u64 v[42:43], s[6:7], 0, v[196:197]
	s_mov_b32 m0, s8
	s_nop 0
	global_load_lds_dwordx4 v[42:43], off
	v_lshl_add_u64 v[42:43], s[6:7], 0, v[198:199]
	s_add_i32 m0, s8, 0x2000
	s_nop 0
	global_load_lds_dwordx4 v[42:43], off
	v_lshl_add_u64 v[42:43], v[246:247], 0, s[24:25]
	s_mov_b32 m0, s63
	s_nop 0
	global_load_lds_dwordx4 v[42:43], off
	v_lshl_add_u64 v[42:43], v[248:249], 0, s[24:25]
	s_mov_b32 m0, s64
	s_nop 0
	global_load_lds_dwordx4 v[42:43], off
	s_waitcnt vmcnt(8)
	s_waitcnt lgkmcnt(0)
	s_barrier
	s_waitcnt lgkmcnt(0)
	v_mfma_i32_16x16x64_i8 v[42:45], v[26:29], v[82:85], v[94:97]
	v_mfma_i32_16x16x64_i8 v[94:97], v[30:33], v[98:101], v[42:45]
	v_mfma_i32_16x16x64_i8 v[42:45], v[34:37], v[82:85], v[90:93]
	v_mfma_i32_16x16x64_i8 v[90:93], v[38:41], v[98:101], v[42:45]
	v_mfma_i32_16x16x64_i8 v[42:45], v[26:29], v[102:105], v[78:81]
	v_mfma_i32_16x16x64_i8 v[78:81], v[30:33], v[106:109], v[42:45]
	v_mfma_i32_16x16x64_i8 v[42:45], v[34:37], v[102:105], v[74:77]
	v_mfma_i32_16x16x64_i8 v[74:77], v[38:41], v[106:109], v[42:45]
	v_mfma_i32_16x16x64_i8 v[42:45], v[26:29], v[110:113], v[62:65]
	v_mfma_i32_16x16x64_i8 v[62:65], v[30:33], v[214:217], v[42:45]
	v_mfma_i32_16x16x64_i8 v[2:5], v[26:29], v[218:221], v[2:5]
	v_mfma_i32_16x16x64_i8 v[46:49], v[30:33], v[222:225], v[2:5]
	v_mfma_i32_16x16x64_i8 v[42:45], v[34:37], v[110:113], v[58:61]
	v_mfma_i32_16x16x64_i8 v[58:61], v[38:41], v[214:217], v[42:45]
	v_mfma_i32_16x16x64_i8 v[2:5], v[34:37], v[218:221], v[6:9]
	v_mfma_i32_16x16x64_i8 v[42:45], v[38:41], v[222:225], v[2:5]
	v_mfma_i32_16x16x64_i8 v[2:5], v[178:181], v[82:85], v[10:13]
	v_mfma_i32_16x16x64_i8 v[86:89], v[182:185], v[98:101], v[2:5]
	v_mfma_i32_16x16x64_i8 v[2:5], v[186:189], v[82:85], v[14:17]
	v_mfma_i32_16x16x64_i8 v[82:85], v[190:193], v[98:101], v[2:5]
	v_mfma_i32_16x16x64_i8 v[2:5], v[178:181], v[102:105], v[70:73]
	v_mfma_i32_16x16x64_i8 v[70:73], v[182:185], v[106:109], v[2:5]
	v_mfma_i32_16x16x64_i8 v[2:5], v[186:189], v[102:105], v[66:69]
	v_mfma_i32_16x16x64_i8 v[66:69], v[190:193], v[106:109], v[2:5]
	v_mfma_i32_16x16x64_i8 v[2:5], v[178:181], v[110:113], v[54:57]
	v_mfma_i32_16x16x64_i8 v[54:57], v[182:185], v[214:217], v[2:5]
	v_mfma_i32_16x16x64_i8 v[2:5], v[186:189], v[110:113], v[50:53]
	v_mfma_i32_16x16x64_i8 v[50:53], v[190:193], v[214:217], v[2:5]
	v_mfma_i32_16x16x64_i8 v[2:5], v[178:181], v[218:221], v[18:21]
	v_mfma_i32_16x16x64_i8 v[38:41], v[182:185], v[222:225], v[2:5]
	v_mfma_i32_16x16x64_i8 v[2:5], v[186:189], v[218:221], v[22:25]
	v_mfma_i32_16x16x64_i8 v[34:37], v[190:193], v[222:225], v[2:5]
	s_barrier
	s_add_i32 s80, s80, 2
	s_add_u32 s4, s4, 0x100
	s_addc_u32 s5, s5, 0
	s_add_u32 s78, s78, 0x100
	s_addc_u32 s79, s79, 0
	s_cmp_gt_u32 s80, 29

.LBB0_1231:
	s_ashr_i32 s23, s22, 31
	s_lshl_b64 s[24:25], s[22:23], 20
	s_add_u32 s24, s17, s24
	s_addc_u32 s25, s36, s25
	s_and_b64 s[26:27], s[0:1], exec
	s_cselect_b32 s23, s25, s29
	s_cselect_b32 s66, s24, s28
	s_ashr_i32 s15, s14, 31
	s_lshl_b64 s[26:27], s[14:15], 20
	s_add_u32 s26, s37, s26
	s_addc_u32 s27, s38, s27
	s_and_b64 s[34:35], s[0:1], exec
	s_cselect_b32 s15, s27, s31
	s_cselect_b32 s67, s26, s30
	s_add_u32 s28, s28, 0x80080
	s_addc_u32 s29, s29, 0
	s_add_u32 s68, s30, 0x100
	s_addc_u32 s69, s31, 0
	s_mov_b32 s70, -2
	ds_read_b128 v[106:109], v197
	ds_read_b128 v[114:117], v197 offset:1024
	ds_read_b128 v[122:125], v197 offset:2048
	ds_read_b128 v[130:133], v197 offset:3072
	ds_read_b128 v[146:149], v201
	ds_read_b128 v[150:153], v201 offset:1024
	ds_read_b128 v[154:157], v201 offset:2048
	ds_read_b128 v[158:161], v201 offset:3072
	s_add_u32 s30, s28, 0xfff80080
	s_addc_u32 s31, s29, -1
	s_cmp_eq_u32 s70, 28
	s_cselect_b32 s35, s23, s31
	s_cselect_b32 s34, s66, s30
	s_cselect_b32 s31, s15, s69
	s_cselect_b32 s30, s67, s68
	v_lshl_add_u64 v[194:195], s[28:29], 0, v[174:175]
	s_add_i32 m0, s19, 0xc000
	ds_read_b128 v[162:165], v204
	ds_read_b128 v[182:185], v204 offset:1024
	ds_read_b128 v[186:189], v204 offset:2048
	ds_read_b128 v[206:209], v204 offset:3072
	ds_read_b128 v[210:213], v204 offset:4096
	ds_read_b128 v[214:217], v204 offset:5120
	ds_read_b128 v[218:221], v204 offset:6144
	ds_read_b128 v[222:225], v204 offset:7168
	global_load_lds_dwordx4 v[194:195], off
	v_lshl_add_u64 v[194:195], s[28:29], 0, v[176:177]
	s_add_i32 m0, s19, 0xe000
	s_nop 0
	global_load_lds_dwordx4 v[194:195], off
	s_waitcnt vmcnt(24)
	s_cmp_lg_u32 s43, 1
	s_cbranch_scc1 .Lrlx1_0
	s_waitcnt vmcnt(8)
.Lrlx1_0:
	s_waitcnt lgkmcnt(0)
	s_barrier
	s_waitcnt lgkmcnt(0)
	v_mfma_i32_16x16x64_i8 v[142:145], v[106:109], v[162:165], 0
	v_mfma_i32_16x16x64_i8 v[142:145], v[114:117], v[182:185], v[142:145]
	v_mfma_i32_16x16x64_i8 v[138:141], v[122:125], v[162:165], 0
	v_mfma_i32_16x16x64_i8 v[138:141], v[130:133], v[182:185], v[138:141]
	v_mfma_i32_16x16x64_i8 v[118:121], v[106:109], v[186:189], 0
	v_mfma_i32_16x16x64_i8 v[118:121], v[114:117], v[206:209], v[118:121]
	v_mfma_i32_16x16x64_i8 v[110:113], v[122:125], v[186:189], 0
	v_mfma_i32_16x16x64_i8 v[110:113], v[130:133], v[206:209], v[110:113]
	v_mfma_i32_16x16x64_i8 v[94:97], v[106:109], v[210:213], 0
	v_mfma_i32_16x16x64_i8 v[94:97], v[114:117], v[214:217], v[94:97]
	v_mfma_i32_16x16x64_i8 v[90:93], v[122:125], v[210:213], 0
	v_mfma_i32_16x16x64_i8 v[90:93], v[130:133], v[214:217], v[90:93]
	v_mfma_i32_16x16x64_i8 v[78:81], v[106:109], v[218:221], 0
	v_mfma_i32_16x16x64_i8 v[78:81], v[114:117], v[222:225], v[78:81]
	v_mfma_i32_16x16x64_i8 v[74:77], v[122:125], v[218:221], 0
	v_mfma_i32_16x16x64_i8 v[74:77], v[130:133], v[222:225], v[74:77]
	v_mfma_i32_16x16x64_i8 v[134:137], v[146:149], v[162:165], 0
	v_mfma_i32_16x16x64_i8 v[134:137], v[150:153], v[182:185], v[134:137]
	v_mfma_i32_16x16x64_i8 v[126:129], v[154:157], v[162:165], 0
	v_mfma_i32_16x16x64_i8 v[126:129], v[158:161], v[182:185], v[126:129]
	v_mfma_i32_16x16x64_i8 v[102:105], v[146:149], v[186:189], 0
	v_mfma_i32_16x16x64_i8 v[102:105], v[150:153], v[206:209], v[102:105]
	v_mfma_i32_16x16x64_i8 v[98:101], v[154:157], v[186:189], 0
	v_mfma_i32_16x16x64_i8 v[98:101], v[158:161], v[206:209], v[98:101]
	v_mfma_i32_16x16x64_i8 v[86:89], v[146:149], v[210:213], 0
	v_mfma_i32_16x16x64_i8 v[86:89], v[150:153], v[214:217], v[86:89]
	v_mfma_i32_16x16x64_i8 v[82:85], v[154:157], v[210:213], 0
	v_mfma_i32_16x16x64_i8 v[82:85], v[158:161], v[214:217], v[82:85]
	v_mfma_i32_16x16x64_i8 v[70:73], v[146:149], v[218:221], 0
	v_mfma_i32_16x16x64_i8 v[70:73], v[150:153], v[222:225], v[70:73]
	v_mfma_i32_16x16x64_i8 v[66:69], v[154:157], v[218:221], 0
	v_mfma_i32_16x16x64_i8 v[66:69], v[158:161], v[222:225], v[66:69]
	s_barrier
	s_add_i32 s71, s63, s39
	v_lshl_add_u64 v[194:195], s[30:31], 0, v[168:169]
	s_mov_b32 m0, s71
	ds_read_b128 v[162:165], v204 offset:16384
	ds_read_b128 v[182:185], v204 offset:17408
	ds_read_b128 v[186:189], v204 offset:18432
	ds_read_b128 v[206:209], v204 offset:19456
	ds_read_b128 v[210:213], v204 offset:20480
	ds_read_b128 v[214:217], v204 offset:21504
	ds_read_b128 v[218:221], v204 offset:22528
	ds_read_b128 v[222:225], v204 offset:23552
	global_load_lds_dwordx4 v[194:195], off
	s_add_i32 m0, s71, 0x2000
	s_add_u32 s72, s30, 0x80000
	v_lshl_add_u64 v[198:199], s[30:31], 0, v[172:173]
	s_addc_u32 s73, s31, 0
	s_add_i32 s71, s64, s39
	global_load_lds_dwordx4 v[198:199], off
	v_lshl_add_u64 v[202:203], s[72:73], 0, v[168:169]
	s_mov_b32 m0, s71
	v_lshl_add_u64 v[226:227], s[34:35], 0, v[170:171]
	global_load_lds_dwordx4 v[202:203], off
	v_lshl_add_u64 v[202:203], s[72:73], 0, v[172:173]
	s_add_i32 m0, s71, 0x2000
	s_nop 0
	global_load_lds_dwordx4 v[202:203], off
	v_lshl_add_u64 v[202:203], s[34:35], 0, v[166:167]
	s_mov_b32 m0, s19
	s_nop 0
	global_load_lds_dwordx4 v[202:203], off
	s_mov_b32 m0, s40
	s_nop 0
	global_load_lds_dwordx4 v[226:227], off
	s_waitcnt vmcnt(24)
	s_cmp_lg_u32 s43, 1
	s_cbranch_scc1 .Lrlx1_1
	s_waitcnt vmcnt(8)
.Lrlx1_1:
	s_waitcnt lgkmcnt(0)
	s_barrier
	s_waitcnt lgkmcnt(0)
	v_mfma_i32_16x16x64_i8 v[62:65], v[106:109], v[162:165], 0
	v_mfma_i32_16x16x64_i8 v[62:65], v[114:117], v[182:185], v[62:65]
	v_mfma_i32_16x16x64_i8 v[58:61], v[122:125], v[162:165], 0
	v_mfma_i32_16x16x64_i8 v[58:61], v[130:133], v[182:185], v[58:61]
	v_mfma_i32_16x16x64_i8 v[46:49], v[106:109], v[186:189], 0
	v_mfma_i32_16x16x64_i8 v[46:49], v[114:117], v[206:209], v[46:49]
	v_mfma_i32_16x16x64_i8 v[42:45], v[122:125], v[186:189], 0
	v_mfma_i32_16x16x64_i8 v[42:45], v[130:133], v[206:209], v[42:45]
	v_mfma_i32_16x16x64_i8 v[30:33], v[106:109], v[210:213], 0
	v_mfma_i32_16x16x64_i8 v[30:33], v[114:117], v[214:217], v[30:33]
	v_mfma_i32_16x16x64_i8 v[26:29], v[122:125], v[210:213], 0
	v_mfma_i32_16x16x64_i8 v[26:29], v[130:133], v[214:217], v[26:29]
	v_mfma_i32_16x16x64_i8 v[14:17], v[106:109], v[218:221], 0
	v_mfma_i32_16x16x64_i8 v[14:17], v[114:117], v[222:225], v[14:17]
	v_mfma_i32_16x16x64_i8 v[10:13], v[122:125], v[218:221], 0
	v_mfma_i32_16x16x64_i8 v[10:13], v[130:133], v[222:225], v[10:13]
	v_mfma_i32_16x16x64_i8 v[54:57], v[146:149], v[162:165], 0
	v_mfma_i32_16x16x64_i8 v[54:57], v[150:153], v[182:185], v[54:57]
	v_mfma_i32_16x16x64_i8 v[50:53], v[154:157], v[162:165], 0
	v_mfma_i32_16x16x64_i8 v[50:53], v[158:161], v[182:185], v[50:53]
	v_mfma_i32_16x16x64_i8 v[38:41], v[146:149], v[186:189], 0
	v_mfma_i32_16x16x64_i8 v[38:41], v[150:153], v[206:209], v[38:41]
	v_mfma_i32_16x16x64_i8 v[34:37], v[154:157], v[186:189], 0
	v_mfma_i32_16x16x64_i8 v[34:37], v[158:161], v[206:209], v[34:37]
	v_mfma_i32_16x16x64_i8 v[22:25], v[146:149], v[210:213], 0
	v_mfma_i32_16x16x64_i8 v[22:25], v[150:153], v[214:217], v[22:25]
	v_mfma_i32_16x16x64_i8 v[18:21], v[154:157], v[210:213], 0
	v_mfma_i32_16x16x64_i8 v[18:21], v[158:161], v[214:217], v[18:21]
	v_mfma_i32_16x16x64_i8 v[6:9], v[146:149], v[218:221], 0
	v_mfma_i32_16x16x64_i8 v[6:9], v[150:153], v[222:225], v[6:9]
	v_mfma_i32_16x16x64_i8 v[2:5], v[154:157], v[218:221], 0
	v_mfma_i32_16x16x64_i8 v[2:5], v[158:161], v[222:225], v[2:5]
	s_barrier
	s_add_i32 s71, 0, 0x18000
	s_add_i32 s72, 0, 0x1c000
	v_add_u32_e32 v130, s71, v193
	v_add_u32_e32 v158, s72, v193
	ds_read_b128 v[106:109], v130
	ds_read_b128 v[114:117], v130 offset:1024
	ds_read_b128 v[122:125], v130 offset:2048
	ds_read_b128 v[130:133], v130 offset:3072
	ds_read_b128 v[146:149], v158
	ds_read_b128 v[150:153], v158 offset:1024
	ds_read_b128 v[154:157], v158 offset:2048
	ds_read_b128 v[158:161], v158 offset:3072
	s_add_u32 s34, s34, 0x80000
	s_addc_u32 s35, s35, 0
	s_mov_b32 m0, s41
	v_lshl_add_u64 v[228:229], s[34:35], 0, v[166:167]
	ds_read_b128 v[162:165], v204 offset:32768
	ds_read_b128 v[182:185], v204 offset:33792
	ds_read_b128 v[186:189], v204 offset:34816
	ds_read_b128 v[206:209], v204 offset:35840
	ds_read_b128 v[210:213], v204 offset:36864
	ds_read_b128 v[214:217], v204 offset:37888
	ds_read_b128 v[218:221], v204 offset:38912
	ds_read_b128 v[222:225], v204 offset:39936
	global_load_lds_dwordx4 v[228:229], off
	v_lshl_add_u64 v[228:229], s[34:35], 0, v[170:171]
	s_mov_b32 m0, s42
	s_nop 0
	global_load_lds_dwordx4 v[228:229], off
	s_waitcnt vmcnt(8)
	s_waitcnt lgkmcnt(0)
	s_barrier
	s_waitcnt lgkmcnt(0)
	v_mfma_i32_16x16x64_i8 v[142:145], v[106:109], v[162:165], v[142:145]
	v_mfma_i32_16x16x64_i8 v[142:145], v[114:117], v[182:185], v[142:145]
	v_mfma_i32_16x16x64_i8 v[138:141], v[122:125], v[162:165], v[138:141]
	v_mfma_i32_16x16x64_i8 v[138:141], v[130:133], v[182:185], v[138:141]
	v_mfma_i32_16x16x64_i8 v[118:121], v[106:109], v[186:189], v[118:121]
	v_mfma_i32_16x16x64_i8 v[118:121], v[114:117], v[206:209], v[118:121]
	v_mfma_i32_16x16x64_i8 v[110:113], v[122:125], v[186:189], v[110:113]
	v_mfma_i32_16x16x64_i8 v[110:113], v[130:133], v[206:209], v[110:113]
	v_mfma_i32_16x16x64_i8 v[94:97], v[106:109], v[210:213], v[94:97]
	v_mfma_i32_16x16x64_i8 v[94:97], v[114:117], v[214:217], v[94:97]
	v_mfma_i32_16x16x64_i8 v[90:93], v[122:125], v[210:213], v[90:93]
	v_mfma_i32_16x16x64_i8 v[90:93], v[130:133], v[214:217], v[90:93]
	v_mfma_i32_16x16x64_i8 v[78:81], v[106:109], v[218:221], v[78:81]
	v_mfma_i32_16x16x64_i8 v[78:81], v[114:117], v[222:225], v[78:81]
	v_mfma_i32_16x16x64_i8 v[74:77], v[122:125], v[218:221], v[74:77]
	v_mfma_i32_16x16x64_i8 v[74:77], v[130:133], v[222:225], v[74:77]
	v_mfma_i32_16x16x64_i8 v[134:137], v[146:149], v[162:165], v[134:137]
	v_mfma_i32_16x16x64_i8 v[134:137], v[150:153], v[182:185], v[134:137]
	v_mfma_i32_16x16x64_i8 v[126:129], v[154:157], v[162:165], v[126:129]
	v_mfma_i32_16x16x64_i8 v[126:129], v[158:161], v[182:185], v[126:129]
	v_mfma_i32_16x16x64_i8 v[102:105], v[146:149], v[186:189], v[102:105]
	v_mfma_i32_16x16x64_i8 v[102:105], v[150:153], v[206:209], v[102:105]
	v_mfma_i32_16x16x64_i8 v[98:101], v[154:157], v[186:189], v[98:101]
	v_mfma_i32_16x16x64_i8 v[98:101], v[158:161], v[206:209], v[98:101]
	v_mfma_i32_16x16x64_i8 v[86:89], v[146:149], v[210:213], v[86:89]
	v_mfma_i32_16x16x64_i8 v[86:89], v[150:153], v[214:217], v[86:89]
	v_mfma_i32_16x16x64_i8 v[82:85], v[154:157], v[210:213], v[82:85]
	v_mfma_i32_16x16x64_i8 v[82:85], v[158:161], v[214:217], v[82:85]
	v_mfma_i32_16x16x64_i8 v[70:73], v[146:149], v[218:221], v[70:73]
	v_mfma_i32_16x16x64_i8 v[70:73], v[150:153], v[222:225], v[70:73]
	v_mfma_i32_16x16x64_i8 v[66:69], v[154:157], v[218:221], v[66:69]
	v_mfma_i32_16x16x64_i8 v[66:69], v[158:161], v[222:225], v[66:69]
	s_barrier
	s_add_i32 s34, s71, s39
	v_lshl_add_u64 v[194:195], v[194:195], 0, s[10:11]
	s_mov_b32 m0, s34
	ds_read_b128 v[162:165], v204 offset:49152
	ds_read_b128 v[182:185], v204 offset:50176
	ds_read_b128 v[186:189], v204 offset:51200
	ds_read_b128 v[206:209], v204 offset:52224
	ds_read_b128 v[210:213], v204 offset:53248
	ds_read_b128 v[214:217], v204 offset:54272
	ds_read_b128 v[218:221], v204 offset:55296
	ds_read_b128 v[222:225], v204 offset:56320
	global_load_lds_dwordx4 v[194:195], off
	s_add_i32 m0, s34, 0x2000
	s_add_u32 s30, s30, 0x80080
	v_lshl_add_u64 v[194:195], v[198:199], 0, s[10:11]
	s_addc_u32 s31, s31, 0
	s_add_i32 s34, s72, s39
	global_load_lds_dwordx4 v[194:195], off
	v_lshl_add_u64 v[194:195], s[30:31], 0, v[168:169]
	s_mov_b32 m0, s34
	s_nop 0
	global_load_lds_dwordx4 v[194:195], off
	v_lshl_add_u64 v[194:195], s[30:31], 0, v[172:173]
	s_add_i32 m0, s34, 0x2000
	s_nop 0
	global_load_lds_dwordx4 v[194:195], off
	v_lshl_add_u64 v[194:195], v[202:203], 0, s[10:11]
	s_mov_b32 m0, s60
	s_nop 0
	global_load_lds_dwordx4 v[194:195], off
	v_lshl_add_u64 v[194:195], v[226:227], 0, s[10:11]
	s_mov_b32 m0, s61
	s_nop 0
	global_load_lds_dwordx4 v[194:195], off
	s_waitcnt vmcnt(8)
	s_waitcnt lgkmcnt(0)
	s_barrier
	s_waitcnt lgkmcnt(0)
	v_mfma_i32_16x16x64_i8 v[62:65], v[106:109], v[162:165], v[62:65]
	v_mfma_i32_16x16x64_i8 v[62:65], v[114:117], v[182:185], v[62:65]
	v_mfma_i32_16x16x64_i8 v[58:61], v[122:125], v[162:165], v[58:61]
	v_mfma_i32_16x16x64_i8 v[58:61], v[130:133], v[182:185], v[58:61]
	v_mfma_i32_16x16x64_i8 v[46:49], v[106:109], v[186:189], v[46:49]
	v_mfma_i32_16x16x64_i8 v[46:49], v[114:117], v[206:209], v[46:49]
	v_mfma_i32_16x16x64_i8 v[42:45], v[122:125], v[186:189], v[42:45]
	v_mfma_i32_16x16x64_i8 v[42:45], v[130:133], v[206:209], v[42:45]
	v_mfma_i32_16x16x64_i8 v[30:33], v[106:109], v[210:213], v[30:33]
	v_mfma_i32_16x16x64_i8 v[30:33], v[114:117], v[214:217], v[30:33]
	v_mfma_i32_16x16x64_i8 v[26:29], v[122:125], v[210:213], v[26:29]
	v_mfma_i32_16x16x64_i8 v[26:29], v[130:133], v[214:217], v[26:29]
	v_mfma_i32_16x16x64_i8 v[14:17], v[106:109], v[218:221], v[14:17]
	v_mfma_i32_16x16x64_i8 v[14:17], v[114:117], v[222:225], v[14:17]
	v_mfma_i32_16x16x64_i8 v[10:13], v[122:125], v[218:221], v[10:13]
	v_mfma_i32_16x16x64_i8 v[10:13], v[130:133], v[222:225], v[10:13]
	v_mfma_i32_16x16x64_i8 v[54:57], v[146:149], v[162:165], v[54:57]
	v_mfma_i32_16x16x64_i8 v[54:57], v[150:153], v[182:185], v[54:57]
	v_mfma_i32_16x16x64_i8 v[50:53], v[154:157], v[162:165], v[50:53]
	v_mfma_i32_16x16x64_i8 v[50:53], v[158:161], v[182:185], v[50:53]
	v_mfma_i32_16x16x64_i8 v[38:41], v[146:149], v[186:189], v[38:41]
	v_mfma_i32_16x16x64_i8 v[38:41], v[150:153], v[206:209], v[38:41]
	v_mfma_i32_16x16x64_i8 v[34:37], v[154:157], v[186:189], v[34:37]
	v_mfma_i32_16x16x64_i8 v[34:37], v[158:161], v[206:209], v[34:37]
	v_mfma_i32_16x16x64_i8 v[22:25], v[146:149], v[210:213], v[22:25]
	v_mfma_i32_16x16x64_i8 v[22:25], v[150:153], v[214:217], v[22:25]
	v_mfma_i32_16x16x64_i8 v[18:21], v[154:157], v[210:213], v[18:21]
	v_mfma_i32_16x16x64_i8 v[18:21], v[158:161], v[214:217], v[18:21]
	v_mfma_i32_16x16x64_i8 v[6:9], v[146:149], v[218:221], v[6:9]
	v_mfma_i32_16x16x64_i8 v[6:9], v[150:153], v[222:225], v[6:9]
	v_mfma_i32_16x16x64_i8 v[2:5], v[154:157], v[218:221], v[2:5]
	v_mfma_i32_16x16x64_i8 v[2:5], v[158:161], v[222:225], v[2:5]
	s_barrier
	s_add_i32 s70, s70, 2
	s_add_u32 s28, s28, 0x100
	s_addc_u32 s29, s29, 0
	s_add_u32 s68, s68, 0x100
	s_addc_u32 s69, s69, 0
	s_cmp_gt_u32 s70, 29

.LBB0_1366:
	s_ashr_i32 s35, s34, 31
	s_lshl_b64 s[18:19], s[34:35], 20
	s_add_u32 s36, s29, s18
	s_addc_u32 s37, s60, s19
	s_and_b64 s[18:19], s[2:3], exec
	s_cselect_b32 s35, s37, s5
	s_cselect_b32 s43, s36, s4
	s_ashr_i32 s31, s30, 31
	s_lshl_b64 s[18:19], s[30:31], 20
	s_add_u32 s38, s61, s18
	s_addc_u32 s39, s62, s19
	s_and_b64 s[18:19], s[2:3], exec
	s_cselect_b32 s31, s39, s7
	s_cselect_b32 vcc_lo, s38, s6
	s_add_u32 vcc_hi, s6, 0x100
	s_addc_u32 s79, s7, 0
	s_mov_b32 s80, -2
	ds_read_b128 v[130:133], v234
	ds_read_b128 v[134:137], v234 offset:1024
	ds_read_b128 v[162:165], v234 offset:2048
	ds_read_b128 v[166:169], v234 offset:3072
	ds_read_b128 v[170:173], v235
	ds_read_b128 v[174:177], v235 offset:1024
	ds_read_b128 v[178:181], v235 offset:2048
	ds_read_b128 v[182:185], v235 offset:3072
	s_add_u32 s6, s4, 0x100
	s_addc_u32 s7, s5, 0
	s_cmp_eq_u32 s80, 28
	s_cselect_b32 s57, s35, s7
	s_cselect_b32 s56, s43, s6
	s_cselect_b32 s19, s31, s79
	s_cselect_b32 s18, vcc_lo, vcc_hi
	v_lshl_add_u64 v[218:219], s[4:5], 0, v[154:155]
	s_add_i32 m0, s65, 0xc000
	ds_read_b128 v[186:189], v236
	ds_read_b128 v[190:193], v236 offset:1024
	ds_read_b128 v[194:197], v236 offset:2048
	ds_read_b128 v[198:201], v236 offset:3072
	ds_read_b128 v[202:205], v236 offset:4096
	ds_read_b128 v[206:209], v236 offset:5120
	ds_read_b128 v[210:213], v236 offset:6144
	ds_read_b128 v[214:217], v236 offset:7168
	global_load_lds_dwordx4 v[218:219], off
	v_lshl_add_u64 v[218:219], s[4:5], 0, v[156:157]
	s_add_i32 m0, s65, 0xe000
	s_nop 0
	global_load_lds_dwordx4 v[218:219], off
	s_waitcnt vmcnt(24)
	s_cmp_lg_u32 s9, 0
	s_cbranch_scc1 .Lrlx2_0
	s_waitcnt vmcnt(8)
.Lrlx2_0:
	s_waitcnt lgkmcnt(0)
	s_barrier
	s_waitcnt lgkmcnt(0)
	v_mfma_i32_16x16x64_i8 v[118:121], v[130:133], v[186:189], 0
	v_mfma_i32_16x16x64_i8 v[118:121], v[134:137], v[190:193], v[118:121]
	v_mfma_i32_16x16x64_i8 v[102:105], v[162:165], v[186:189], 0
	v_mfma_i32_16x16x64_i8 v[102:105], v[166:169], v[190:193], v[102:105]
	v_mfma_i32_16x16x64_i8 v[114:117], v[130:133], v[194:197], 0
	v_mfma_i32_16x16x64_i8 v[114:117], v[134:137], v[198:201], v[114:117]
	v_mfma_i32_16x16x64_i8 v[98:101], v[162:165], v[194:197], 0
	v_mfma_i32_16x16x64_i8 v[98:101], v[166:169], v[198:201], v[98:101]
	v_mfma_i32_16x16x64_i8 v[126:129], v[130:133], v[202:205], 0
	v_mfma_i32_16x16x64_i8 v[126:129], v[134:137], v[206:209], v[126:129]
	v_mfma_i32_16x16x64_i8 v[110:113], v[162:165], v[202:205], 0
	v_mfma_i32_16x16x64_i8 v[110:113], v[166:169], v[206:209], v[110:113]
	v_mfma_i32_16x16x64_i8 v[122:125], v[130:133], v[210:213], 0
	v_mfma_i32_16x16x64_i8 v[122:125], v[134:137], v[214:217], v[122:125]
	v_mfma_i32_16x16x64_i8 v[106:109], v[162:165], v[210:213], 0
	v_mfma_i32_16x16x64_i8 v[106:109], v[166:169], v[214:217], v[106:109]
	v_mfma_i32_16x16x64_i8 v[86:89], v[170:173], v[186:189], 0
	v_mfma_i32_16x16x64_i8 v[86:89], v[174:177], v[190:193], v[86:89]
	v_mfma_i32_16x16x64_i8 v[70:73], v[178:181], v[186:189], 0
	v_mfma_i32_16x16x64_i8 v[70:73], v[182:185], v[190:193], v[70:73]
	v_mfma_i32_16x16x64_i8 v[82:85], v[170:173], v[194:197], 0
	v_mfma_i32_16x16x64_i8 v[82:85], v[174:177], v[198:201], v[82:85]
	v_mfma_i32_16x16x64_i8 v[66:69], v[178:181], v[194:197], 0
	v_mfma_i32_16x16x64_i8 v[66:69], v[182:185], v[198:201], v[66:69]
	v_mfma_i32_16x16x64_i8 v[94:97], v[170:173], v[202:205], 0
	v_mfma_i32_16x16x64_i8 v[94:97], v[174:177], v[206:209], v[94:97]
	v_mfma_i32_16x16x64_i8 v[78:81], v[178:181], v[202:205], 0
	v_mfma_i32_16x16x64_i8 v[78:81], v[182:185], v[206:209], v[78:81]
	v_mfma_i32_16x16x64_i8 v[90:93], v[170:173], v[210:213], 0
	v_mfma_i32_16x16x64_i8 v[90:93], v[174:177], v[214:217], v[90:93]
	v_mfma_i32_16x16x64_i8 v[74:77], v[178:181], v[210:213], 0
	v_mfma_i32_16x16x64_i8 v[74:77], v[182:185], v[214:217], v[74:77]
	s_barrier
	s_add_i32 s4, s97, s63
	v_lshl_add_u64 v[218:219], s[18:19], 0, v[144:145]
	s_mov_b32 m0, s4
	ds_read_b128 v[186:189], v236 offset:16384
	ds_read_b128 v[190:193], v236 offset:17408
	ds_read_b128 v[194:197], v236 offset:18432
	ds_read_b128 v[198:201], v236 offset:19456
	ds_read_b128 v[202:205], v236 offset:20480
	ds_read_b128 v[206:209], v236 offset:21504
	ds_read_b128 v[210:213], v236 offset:22528
	ds_read_b128 v[214:217], v236 offset:23552
	global_load_lds_dwordx4 v[218:219], off
	s_add_i32 m0, s4, 0x2000
	s_add_u32 s4, s18, 0x80000
	v_lshl_add_u64 v[220:221], s[18:19], 0, v[148:149]
	s_addc_u32 s5, s19, 0
	s_add_i32 s81, s0, s63
	global_load_lds_dwordx4 v[220:221], off
	v_lshl_add_u64 v[222:223], s[4:5], 0, v[144:145]
	s_mov_b32 m0, s81
	v_lshl_add_u64 v[224:225], s[56:57], 0, v[146:147]
	global_load_lds_dwordx4 v[222:223], off
	v_lshl_add_u64 v[222:223], s[4:5], 0, v[148:149]
	s_add_i32 m0, s81, 0x2000
	s_nop 0
	global_load_lds_dwordx4 v[222:223], off
	v_lshl_add_u64 v[222:223], s[56:57], 0, v[142:143]
	s_mov_b32 m0, s65
	s_nop 0
	global_load_lds_dwordx4 v[222:223], off
	s_mov_b32 m0, s66
	s_nop 0
	global_load_lds_dwordx4 v[224:225], off
	s_waitcnt vmcnt(24)
	s_cmp_lg_u32 s9, 0
	s_cbranch_scc1 .Lrlx2_1
	s_waitcnt vmcnt(8)
.Lrlx2_1:
	s_waitcnt lgkmcnt(0)
	s_barrier
	s_waitcnt lgkmcnt(0)
	v_mfma_i32_16x16x64_i8 v[54:57], v[130:133], v[186:189], 0
	v_mfma_i32_16x16x64_i8 v[54:57], v[134:137], v[190:193], v[54:57]
	v_mfma_i32_16x16x64_i8 v[18:21], v[162:165], v[186:189], 0
	v_mfma_i32_16x16x64_i8 v[18:21], v[166:169], v[190:193], v[18:21]
	v_mfma_i32_16x16x64_i8 v[50:53], v[130:133], v[194:197], 0
	v_mfma_i32_16x16x64_i8 v[50:53], v[134:137], v[198:201], v[50:53]
	v_mfma_i32_16x16x64_i8 v[22:25], v[162:165], v[194:197], 0
	v_mfma_i32_16x16x64_i8 v[22:25], v[166:169], v[198:201], v[22:25]
	v_mfma_i32_16x16x64_i8 v[62:65], v[130:133], v[202:205], 0
	v_mfma_i32_16x16x64_i8 v[62:65], v[134:137], v[206:209], v[62:65]
	v_mfma_i32_16x16x64_i8 v[30:33], v[162:165], v[202:205], 0
	v_mfma_i32_16x16x64_i8 v[30:33], v[166:169], v[206:209], v[30:33]
	v_mfma_i32_16x16x64_i8 v[58:61], v[130:133], v[210:213], 0
	v_mfma_i32_16x16x64_i8 v[58:61], v[134:137], v[214:217], v[58:61]
	v_mfma_i32_16x16x64_i8 v[26:29], v[162:165], v[210:213], 0
	v_mfma_i32_16x16x64_i8 v[26:29], v[166:169], v[214:217], v[26:29]
	v_mfma_i32_16x16x64_i8 v[46:49], v[170:173], v[186:189], 0
	v_mfma_i32_16x16x64_i8 v[46:49], v[174:177], v[190:193], v[46:49]
	v_mfma_i32_16x16x64_i8 v[14:17], v[178:181], v[186:189], 0
	v_mfma_i32_16x16x64_i8 v[14:17], v[182:185], v[190:193], v[14:17]
	v_mfma_i32_16x16x64_i8 v[42:45], v[170:173], v[194:197], 0
	v_mfma_i32_16x16x64_i8 v[42:45], v[174:177], v[198:201], v[42:45]
	v_mfma_i32_16x16x64_i8 v[10:13], v[178:181], v[194:197], 0
	v_mfma_i32_16x16x64_i8 v[10:13], v[182:185], v[198:201], v[10:13]
	v_mfma_i32_16x16x64_i8 v[38:41], v[170:173], v[202:205], 0
	v_mfma_i32_16x16x64_i8 v[38:41], v[174:177], v[206:209], v[38:41]
	v_mfma_i32_16x16x64_i8 v[6:9], v[178:181], v[202:205], 0
	v_mfma_i32_16x16x64_i8 v[6:9], v[182:185], v[206:209], v[6:9]
	v_mfma_i32_16x16x64_i8 v[34:37], v[170:173], v[210:213], 0
	v_mfma_i32_16x16x64_i8 v[34:37], v[174:177], v[214:217], v[34:37]
	v_mfma_i32_16x16x64_i8 v[2:5], v[178:181], v[210:213], 0
	v_mfma_i32_16x16x64_i8 v[2:5], v[182:185], v[214:217], v[2:5]
	s_barrier
	s_add_i32 s81, 0, 0x18000
	s_add_i32 s82, 0, 0x1c000
	v_add_u32_e32 v166, s81, v232
	v_add_u32_e32 v182, s82, v232
	ds_read_b128 v[130:133], v166
	ds_read_b128 v[134:137], v166 offset:1024
	ds_read_b128 v[162:165], v166 offset:2048
	ds_read_b128 v[166:169], v166 offset:3072
	ds_read_b128 v[170:173], v182
	ds_read_b128 v[174:177], v182 offset:1024
	ds_read_b128 v[178:181], v182 offset:2048
	ds_read_b128 v[182:185], v182 offset:3072
	s_add_u32 s4, s56, 0x80000
	s_addc_u32 s5, s57, 0
	s_mov_b32 m0, s67
	v_lshl_add_u64 v[226:227], s[4:5], 0, v[142:143]
	ds_read_b128 v[186:189], v236 offset:32768
	ds_read_b128 v[190:193], v236 offset:33792
	ds_read_b128 v[194:197], v236 offset:34816
	ds_read_b128 v[198:201], v236 offset:35840
	ds_read_b128 v[202:205], v236 offset:36864
	ds_read_b128 v[206:209], v236 offset:37888
	ds_read_b128 v[210:213], v236 offset:38912
	ds_read_b128 v[214:217], v236 offset:39936
	global_load_lds_dwordx4 v[226:227], off
	v_lshl_add_u64 v[226:227], s[4:5], 0, v[146:147]
	s_mov_b32 m0, s68
	s_nop 0
	global_load_lds_dwordx4 v[226:227], off
	s_waitcnt vmcnt(8)
	s_waitcnt lgkmcnt(0)
	s_barrier
	s_waitcnt lgkmcnt(0)
	v_mfma_i32_16x16x64_i8 v[118:121], v[130:133], v[186:189], v[118:121]
	v_mfma_i32_16x16x64_i8 v[118:121], v[134:137], v[190:193], v[118:121]
	v_mfma_i32_16x16x64_i8 v[102:105], v[162:165], v[186:189], v[102:105]
	v_mfma_i32_16x16x64_i8 v[102:105], v[166:169], v[190:193], v[102:105]
	v_mfma_i32_16x16x64_i8 v[114:117], v[130:133], v[194:197], v[114:117]
	v_mfma_i32_16x16x64_i8 v[114:117], v[134:137], v[198:201], v[114:117]
	v_mfma_i32_16x16x64_i8 v[98:101], v[162:165], v[194:197], v[98:101]
	v_mfma_i32_16x16x64_i8 v[98:101], v[166:169], v[198:201], v[98:101]
	v_mfma_i32_16x16x64_i8 v[126:129], v[130:133], v[202:205], v[126:129]
	v_mfma_i32_16x16x64_i8 v[126:129], v[134:137], v[206:209], v[126:129]
	v_mfma_i32_16x16x64_i8 v[110:113], v[162:165], v[202:205], v[110:113]
	v_mfma_i32_16x16x64_i8 v[110:113], v[166:169], v[206:209], v[110:113]
	v_mfma_i32_16x16x64_i8 v[122:125], v[130:133], v[210:213], v[122:125]
	v_mfma_i32_16x16x64_i8 v[122:125], v[134:137], v[214:217], v[122:125]
	v_mfma_i32_16x16x64_i8 v[106:109], v[162:165], v[210:213], v[106:109]
	v_mfma_i32_16x16x64_i8 v[106:109], v[166:169], v[214:217], v[106:109]
	v_mfma_i32_16x16x64_i8 v[86:89], v[170:173], v[186:189], v[86:89]
	v_mfma_i32_16x16x64_i8 v[86:89], v[174:177], v[190:193], v[86:89]
	v_mfma_i32_16x16x64_i8 v[70:73], v[178:181], v[186:189], v[70:73]
	v_mfma_i32_16x16x64_i8 v[70:73], v[182:185], v[190:193], v[70:73]
	v_mfma_i32_16x16x64_i8 v[82:85], v[170:173], v[194:197], v[82:85]
	v_mfma_i32_16x16x64_i8 v[82:85], v[174:177], v[198:201], v[82:85]
	v_mfma_i32_16x16x64_i8 v[66:69], v[178:181], v[194:197], v[66:69]
	v_mfma_i32_16x16x64_i8 v[66:69], v[182:185], v[198:201], v[66:69]
	v_mfma_i32_16x16x64_i8 v[94:97], v[170:173], v[202:205], v[94:97]
	v_mfma_i32_16x16x64_i8 v[94:97], v[174:177], v[206:209], v[94:97]
	v_mfma_i32_16x16x64_i8 v[78:81], v[178:181], v[202:205], v[78:81]
	v_mfma_i32_16x16x64_i8 v[78:81], v[182:185], v[206:209], v[78:81]
	v_mfma_i32_16x16x64_i8 v[90:93], v[170:173], v[210:213], v[90:93]
	v_mfma_i32_16x16x64_i8 v[90:93], v[174:177], v[214:217], v[90:93]
	v_mfma_i32_16x16x64_i8 v[74:77], v[178:181], v[210:213], v[74:77]
	v_mfma_i32_16x16x64_i8 v[74:77], v[182:185], v[214:217], v[74:77]
	s_barrier
	s_add_i32 s4, s81, s63
	v_lshl_add_u64 v[218:219], v[218:219], 0, s[22:23]
	s_mov_b32 m0, s4
	ds_read_b128 v[186:189], v236 offset:49152
	ds_read_b128 v[190:193], v236 offset:50176
	ds_read_b128 v[194:197], v236 offset:51200
	ds_read_b128 v[198:201], v236 offset:52224
	ds_read_b128 v[202:205], v236 offset:53248
	ds_read_b128 v[206:209], v236 offset:54272
	ds_read_b128 v[210:213], v236 offset:55296
	ds_read_b128 v[214:217], v236 offset:56320
	global_load_lds_dwordx4 v[218:219], off
	s_add_i32 m0, s4, 0x2000
	s_add_u32 s4, s18, 0x80080
	v_lshl_add_u64 v[218:219], v[220:221], 0, s[22:23]
	s_addc_u32 s5, s19, 0
	s_add_i32 s18, s82, s63
	global_load_lds_dwordx4 v[218:219], off
	v_lshl_add_u64 v[218:219], s[4:5], 0, v[144:145]
	s_mov_b32 m0, s18
	s_nop 0
	global_load_lds_dwordx4 v[218:219], off
	v_lshl_add_u64 v[218:219], s[4:5], 0, v[148:149]
	s_add_i32 m0, s18, 0x2000
	s_nop 0
	global_load_lds_dwordx4 v[218:219], off
	v_lshl_add_u64 v[218:219], v[222:223], 0, s[22:23]
	s_mov_b32 m0, s77
	s_nop 0
	global_load_lds_dwordx4 v[218:219], off
	v_lshl_add_u64 v[218:219], v[224:225], 0, s[22:23]
	s_mov_b32 m0, s78
	s_nop 0
	global_load_lds_dwordx4 v[218:219], off
	s_waitcnt vmcnt(8)
	s_waitcnt lgkmcnt(0)
	s_barrier
	s_waitcnt lgkmcnt(0)
	v_mfma_i32_16x16x64_i8 v[54:57], v[130:133], v[186:189], v[54:57]
	v_mfma_i32_16x16x64_i8 v[54:57], v[134:137], v[190:193], v[54:57]
	v_mfma_i32_16x16x64_i8 v[18:21], v[162:165], v[186:189], v[18:21]
	v_mfma_i32_16x16x64_i8 v[18:21], v[166:169], v[190:193], v[18:21]
	v_mfma_i32_16x16x64_i8 v[50:53], v[130:133], v[194:197], v[50:53]
	v_mfma_i32_16x16x64_i8 v[50:53], v[134:137], v[198:201], v[50:53]
	v_mfma_i32_16x16x64_i8 v[22:25], v[162:165], v[194:197], v[22:25]
	v_mfma_i32_16x16x64_i8 v[22:25], v[166:169], v[198:201], v[22:25]
	v_mfma_i32_16x16x64_i8 v[62:65], v[130:133], v[202:205], v[62:65]
	v_mfma_i32_16x16x64_i8 v[62:65], v[134:137], v[206:209], v[62:65]
	v_mfma_i32_16x16x64_i8 v[30:33], v[162:165], v[202:205], v[30:33]
	v_mfma_i32_16x16x64_i8 v[30:33], v[166:169], v[206:209], v[30:33]
	v_mfma_i32_16x16x64_i8 v[58:61], v[130:133], v[210:213], v[58:61]
	v_mfma_i32_16x16x64_i8 v[58:61], v[134:137], v[214:217], v[58:61]
	v_mfma_i32_16x16x64_i8 v[26:29], v[162:165], v[210:213], v[26:29]
	v_mfma_i32_16x16x64_i8 v[26:29], v[166:169], v[214:217], v[26:29]
	v_mfma_i32_16x16x64_i8 v[46:49], v[170:173], v[186:189], v[46:49]
	v_mfma_i32_16x16x64_i8 v[46:49], v[174:177], v[190:193], v[46:49]
	v_mfma_i32_16x16x64_i8 v[14:17], v[178:181], v[186:189], v[14:17]
	v_mfma_i32_16x16x64_i8 v[14:17], v[182:185], v[190:193], v[14:17]
	v_mfma_i32_16x16x64_i8 v[42:45], v[170:173], v[194:197], v[42:45]
	v_mfma_i32_16x16x64_i8 v[42:45], v[174:177], v[198:201], v[42:45]
	v_mfma_i32_16x16x64_i8 v[10:13], v[178:181], v[194:197], v[10:13]
	v_mfma_i32_16x16x64_i8 v[10:13], v[182:185], v[198:201], v[10:13]
	v_mfma_i32_16x16x64_i8 v[38:41], v[170:173], v[202:205], v[38:41]
	v_mfma_i32_16x16x64_i8 v[38:41], v[174:177], v[206:209], v[38:41]
	v_mfma_i32_16x16x64_i8 v[6:9], v[178:181], v[202:205], v[6:9]
	v_mfma_i32_16x16x64_i8 v[6:9], v[182:185], v[206:209], v[6:9]
	v_mfma_i32_16x16x64_i8 v[34:37], v[170:173], v[210:213], v[34:37]
	v_mfma_i32_16x16x64_i8 v[34:37], v[174:177], v[214:217], v[34:37]
	v_mfma_i32_16x16x64_i8 v[2:5], v[178:181], v[210:213], v[2:5]
	v_mfma_i32_16x16x64_i8 v[2:5], v[182:185], v[214:217], v[2:5]
	s_barrier
	s_add_i32 s80, s80, 2
	s_add_u32 vcc_hi, vcc_hi, 0x100
	s_addc_u32 s79, s79, 0
	s_cmp_gt_u32 s80, 29
	s_mov_b64 s[4:5], s[6:7]

.LBB0_1553:
	s_add_u32 s64, s26, 0x100
	s_addc_u32 s65, s27, 0
	s_mov_b32 s66, -2
	s_waitcnt lgkmcnt(0)
	ds_read_b128 v[114:117], v247
	ds_read_b128 v[118:121], v247 offset:1024
	ds_read_b128 v[126:129], v247 offset:2048
	ds_read_b128 v[134:137], v247 offset:3072
	ds_read_b128 v[138:141], v248
	ds_read_b128 v[142:145], v248 offset:1024
	ds_read_b128 v[154:157], v248 offset:2048
	ds_read_b128 v[158:161], v248 offset:3072
	s_add_u32 s4, s18, 0x100
	s_addc_u32 s5, s19, 0
	s_cmpk_eq_i32 s66, 0xdc
	s_cselect_b32 s29, s23, s5
	s_cselect_b32 s28, s22, s4
	s_cselect_b32 s27, s25, s65
	s_cselect_b32 s26, s24, s64
	v_lshl_add_u64 v[210:211], s[18:19], 0, v[202:203]
	s_add_i32 m0, s17, 0xc000
	ds_read_b128 v[162:165], v249
	ds_read_b128 v[166:169], v249 offset:1024
	ds_read_b128 v[170:173], v249 offset:2048
	ds_read_b128 v[174:177], v249 offset:3072
	ds_read_b128 v[178:181], v249 offset:4096
	ds_read_b128 v[182:185], v249 offset:5120
	ds_read_b128 v[186:189], v249 offset:6144
	ds_read_b128 v[190:193], v249 offset:7168
	global_load_lds_dwordx4 v[210:211], off
	v_lshl_add_u64 v[210:211], s[18:19], 0, v[204:205]
	s_add_i32 m0, s17, 0xe000
	s_nop 0
	global_load_lds_dwordx4 v[210:211], off
	s_waitcnt vmcnt(24)
	s_cmp_lg_u32 s35, 1
	s_cbranch_scc1 .Lrlx3_0
	s_waitcnt vmcnt(8)
.Lrlx3_0:
	s_waitcnt lgkmcnt(0)
	s_barrier
	s_waitcnt lgkmcnt(0)
	v_mfma_f32_16x16x32_bf16 v[150:153], v[114:117], v[162:165], 0
	v_mfma_f32_16x16x32_bf16 v[150:153], v[118:121], v[166:169], v[150:153]
	v_mfma_f32_16x16x32_bf16 v[146:149], v[126:129], v[162:165], 0
	v_mfma_f32_16x16x32_bf16 v[146:149], v[134:137], v[166:169], v[146:149]
	v_mfma_f32_16x16x32_bf16 v[110:113], v[114:117], v[170:173], 0
	v_mfma_f32_16x16x32_bf16 v[110:113], v[118:121], v[174:177], v[110:113]
	v_mfma_f32_16x16x32_bf16 v[106:109], v[126:129], v[170:173], 0
	v_mfma_f32_16x16x32_bf16 v[106:109], v[134:137], v[174:177], v[106:109]
	v_mfma_f32_16x16x32_bf16 v[94:97], v[114:117], v[178:181], 0
	v_mfma_f32_16x16x32_bf16 v[94:97], v[118:121], v[182:185], v[94:97]
	v_mfma_f32_16x16x32_bf16 v[90:93], v[126:129], v[178:181], 0
	v_mfma_f32_16x16x32_bf16 v[90:93], v[134:137], v[182:185], v[90:93]
	v_mfma_f32_16x16x32_bf16 v[78:81], v[114:117], v[186:189], 0
	v_mfma_f32_16x16x32_bf16 v[78:81], v[118:121], v[190:193], v[78:81]
	v_mfma_f32_16x16x32_bf16 v[74:77], v[126:129], v[186:189], 0
	v_mfma_f32_16x16x32_bf16 v[74:77], v[134:137], v[190:193], v[74:77]
	v_mfma_f32_16x16x32_bf16 v[130:133], v[138:141], v[162:165], 0
	v_mfma_f32_16x16x32_bf16 v[130:133], v[142:145], v[166:169], v[130:133]
	v_mfma_f32_16x16x32_bf16 v[122:125], v[154:157], v[162:165], 0
	v_mfma_f32_16x16x32_bf16 v[122:125], v[158:161], v[166:169], v[122:125]
	v_mfma_f32_16x16x32_bf16 v[102:105], v[138:141], v[170:173], 0
	v_mfma_f32_16x16x32_bf16 v[102:105], v[142:145], v[174:177], v[102:105]
	v_mfma_f32_16x16x32_bf16 v[98:101], v[154:157], v[170:173], 0
	v_mfma_f32_16x16x32_bf16 v[98:101], v[158:161], v[174:177], v[98:101]
	v_mfma_f32_16x16x32_bf16 v[86:89], v[138:141], v[178:181], 0
	v_mfma_f32_16x16x32_bf16 v[86:89], v[142:145], v[182:185], v[86:89]
	v_mfma_f32_16x16x32_bf16 v[82:85], v[154:157], v[178:181], 0
	v_mfma_f32_16x16x32_bf16 v[82:85], v[158:161], v[182:185], v[82:85]
	v_mfma_f32_16x16x32_bf16 v[70:73], v[138:141], v[186:189], 0
	v_mfma_f32_16x16x32_bf16 v[70:73], v[142:145], v[190:193], v[70:73]
	v_mfma_f32_16x16x32_bf16 v[66:69], v[154:157], v[186:189], 0
	v_mfma_f32_16x16x32_bf16 v[66:69], v[158:161], v[190:193], v[66:69]
	s_barrier
	s_add_i32 s18, s42, s16
	v_lshl_add_u64 v[210:211], s[26:27], 0, v[196:197]
	s_mov_b32 m0, s18
	ds_read_b128 v[162:165], v249 offset:16384
	ds_read_b128 v[166:169], v249 offset:17408
	ds_read_b128 v[170:173], v249 offset:18432
	ds_read_b128 v[174:177], v249 offset:19456
	ds_read_b128 v[178:181], v249 offset:20480
	ds_read_b128 v[182:185], v249 offset:21504
	ds_read_b128 v[186:189], v249 offset:22528
	ds_read_b128 v[190:193], v249 offset:23552
	global_load_lds_dwordx4 v[210:211], off
	s_add_i32 m0, s18, 0x2000
	s_add_u32 s18, s26, 0x380000
	v_lshl_add_u64 v[212:213], s[26:27], 0, v[200:201]
	s_addc_u32 s19, s27, 0
	s_add_i32 s67, s43, s16
	global_load_lds_dwordx4 v[212:213], off
	v_lshl_add_u64 v[214:215], s[18:19], 0, v[196:197]
	s_mov_b32 m0, s67
	v_lshl_add_u64 v[216:217], s[28:29], 0, v[198:199]
	global_load_lds_dwordx4 v[214:215], off
	v_lshl_add_u64 v[214:215], s[18:19], 0, v[200:201]
	s_add_i32 m0, s67, 0x2000
	s_nop 0
	global_load_lds_dwordx4 v[214:215], off
	v_lshl_add_u64 v[214:215], s[28:29], 0, v[194:195]
	s_mov_b32 m0, s17
	s_nop 0
	global_load_lds_dwordx4 v[214:215], off
	s_mov_b32 m0, s30
	s_nop 0
	global_load_lds_dwordx4 v[216:217], off
	s_waitcnt vmcnt(24)
	s_cmp_lg_u32 s35, 1
	s_cbranch_scc1 .Lrlx3_1
	s_waitcnt vmcnt(8)
.Lrlx3_1:
	s_waitcnt lgkmcnt(0)
	s_barrier
	s_waitcnt lgkmcnt(0)
	v_mfma_f32_16x16x32_bf16 v[62:65], v[114:117], v[162:165], 0
	v_mfma_f32_16x16x32_bf16 v[62:65], v[118:121], v[166:169], v[62:65]
	v_mfma_f32_16x16x32_bf16 v[58:61], v[126:129], v[162:165], 0
	v_mfma_f32_16x16x32_bf16 v[58:61], v[134:137], v[166:169], v[58:61]
	v_mfma_f32_16x16x32_bf16 v[46:49], v[114:117], v[170:173], 0
	v_mfma_f32_16x16x32_bf16 v[46:49], v[118:121], v[174:177], v[46:49]
	v_mfma_f32_16x16x32_bf16 v[42:45], v[126:129], v[170:173], 0
	v_mfma_f32_16x16x32_bf16 v[42:45], v[134:137], v[174:177], v[42:45]
	v_mfma_f32_16x16x32_bf16 v[30:33], v[114:117], v[178:181], 0
	v_mfma_f32_16x16x32_bf16 v[30:33], v[118:121], v[182:185], v[30:33]
	v_mfma_f32_16x16x32_bf16 v[26:29], v[126:129], v[178:181], 0
	v_mfma_f32_16x16x32_bf16 v[26:29], v[134:137], v[182:185], v[26:29]
	v_mfma_f32_16x16x32_bf16 v[14:17], v[114:117], v[186:189], 0
	v_mfma_f32_16x16x32_bf16 v[14:17], v[118:121], v[190:193], v[14:17]
	v_mfma_f32_16x16x32_bf16 v[10:13], v[126:129], v[186:189], 0
	v_mfma_f32_16x16x32_bf16 v[10:13], v[134:137], v[190:193], v[10:13]
	v_mfma_f32_16x16x32_bf16 v[54:57], v[138:141], v[162:165], 0
	v_mfma_f32_16x16x32_bf16 v[54:57], v[142:145], v[166:169], v[54:57]
	v_mfma_f32_16x16x32_bf16 v[50:53], v[154:157], v[162:165], 0
	v_mfma_f32_16x16x32_bf16 v[50:53], v[158:161], v[166:169], v[50:53]
	v_mfma_f32_16x16x32_bf16 v[38:41], v[138:141], v[170:173], 0
	v_mfma_f32_16x16x32_bf16 v[38:41], v[142:145], v[174:177], v[38:41]
	v_mfma_f32_16x16x32_bf16 v[34:37], v[154:157], v[170:173], 0
	v_mfma_f32_16x16x32_bf16 v[34:37], v[158:161], v[174:177], v[34:37]
	v_mfma_f32_16x16x32_bf16 v[22:25], v[138:141], v[178:181], 0
	v_mfma_f32_16x16x32_bf16 v[22:25], v[142:145], v[182:185], v[22:25]
	v_mfma_f32_16x16x32_bf16 v[18:21], v[154:157], v[178:181], 0
	v_mfma_f32_16x16x32_bf16 v[18:21], v[158:161], v[182:185], v[18:21]
	v_mfma_f32_16x16x32_bf16 v[6:9], v[138:141], v[186:189], 0
	v_mfma_f32_16x16x32_bf16 v[6:9], v[142:145], v[190:193], v[6:9]
	v_mfma_f32_16x16x32_bf16 v[2:5], v[154:157], v[186:189], 0
	v_mfma_f32_16x16x32_bf16 v[2:5], v[158:161], v[190:193], v[2:5]
	s_barrier
	s_add_i32 s67, 0, 0x18000
	s_add_i32 s68, 0, 0x1c000
	v_add_u32_e32 v134, s67, v244
	v_add_u32_e32 v158, s68, v244
	ds_read_b128 v[114:117], v134
	ds_read_b128 v[118:121], v134 offset:1024
	ds_read_b128 v[126:129], v134 offset:2048
	ds_read_b128 v[134:137], v134 offset:3072
	ds_read_b128 v[138:141], v158
	ds_read_b128 v[142:145], v158 offset:1024
	ds_read_b128 v[154:157], v158 offset:2048
	ds_read_b128 v[158:161], v158 offset:3072
	s_add_u32 s18, s28, 0x380000
	s_addc_u32 s19, s29, 0
	s_mov_b32 m0, s31
	v_lshl_add_u64 v[218:219], s[18:19], 0, v[194:195]
	ds_read_b128 v[162:165], v249 offset:32768
	ds_read_b128 v[166:169], v249 offset:33792
	ds_read_b128 v[170:173], v249 offset:34816
	ds_read_b128 v[174:177], v249 offset:35840
	ds_read_b128 v[178:181], v249 offset:36864
	ds_read_b128 v[182:185], v249 offset:37888
	ds_read_b128 v[186:189], v249 offset:38912
	ds_read_b128 v[190:193], v249 offset:39936
	global_load_lds_dwordx4 v[218:219], off
	v_lshl_add_u64 v[218:219], s[18:19], 0, v[198:199]
	s_mov_b32 m0, s34
	s_nop 0
	global_load_lds_dwordx4 v[218:219], off
	s_waitcnt vmcnt(8)
	s_waitcnt lgkmcnt(0)
	s_barrier
	s_waitcnt lgkmcnt(0)
	v_mfma_f32_16x16x32_bf16 v[150:153], v[114:117], v[162:165], v[150:153]
	v_mfma_f32_16x16x32_bf16 v[150:153], v[118:121], v[166:169], v[150:153]
	v_mfma_f32_16x16x32_bf16 v[146:149], v[126:129], v[162:165], v[146:149]
	v_mfma_f32_16x16x32_bf16 v[146:149], v[134:137], v[166:169], v[146:149]
	v_mfma_f32_16x16x32_bf16 v[110:113], v[114:117], v[170:173], v[110:113]
	v_mfma_f32_16x16x32_bf16 v[110:113], v[118:121], v[174:177], v[110:113]
	v_mfma_f32_16x16x32_bf16 v[106:109], v[126:129], v[170:173], v[106:109]
	v_mfma_f32_16x16x32_bf16 v[106:109], v[134:137], v[174:177], v[106:109]
	v_mfma_f32_16x16x32_bf16 v[94:97], v[114:117], v[178:181], v[94:97]
	v_mfma_f32_16x16x32_bf16 v[94:97], v[118:121], v[182:185], v[94:97]
	v_mfma_f32_16x16x32_bf16 v[90:93], v[126:129], v[178:181], v[90:93]
	v_mfma_f32_16x16x32_bf16 v[90:93], v[134:137], v[182:185], v[90:93]
	v_mfma_f32_16x16x32_bf16 v[78:81], v[114:117], v[186:189], v[78:81]
	v_mfma_f32_16x16x32_bf16 v[78:81], v[118:121], v[190:193], v[78:81]
	v_mfma_f32_16x16x32_bf16 v[74:77], v[126:129], v[186:189], v[74:77]
	v_mfma_f32_16x16x32_bf16 v[74:77], v[134:137], v[190:193], v[74:77]
	v_mfma_f32_16x16x32_bf16 v[130:133], v[138:141], v[162:165], v[130:133]
	v_mfma_f32_16x16x32_bf16 v[130:133], v[142:145], v[166:169], v[130:133]
	v_mfma_f32_16x16x32_bf16 v[122:125], v[154:157], v[162:165], v[122:125]
	v_mfma_f32_16x16x32_bf16 v[122:125], v[158:161], v[166:169], v[122:125]
	v_mfma_f32_16x16x32_bf16 v[102:105], v[138:141], v[170:173], v[102:105]
	v_mfma_f32_16x16x32_bf16 v[102:105], v[142:145], v[174:177], v[102:105]
	v_mfma_f32_16x16x32_bf16 v[98:101], v[154:157], v[170:173], v[98:101]
	v_mfma_f32_16x16x32_bf16 v[98:101], v[158:161], v[174:177], v[98:101]
	v_mfma_f32_16x16x32_bf16 v[86:89], v[138:141], v[178:181], v[86:89]
	v_mfma_f32_16x16x32_bf16 v[86:89], v[142:145], v[182:185], v[86:89]
	v_mfma_f32_16x16x32_bf16 v[82:85], v[154:157], v[178:181], v[82:85]
	v_mfma_f32_16x16x32_bf16 v[82:85], v[158:161], v[182:185], v[82:85]
	v_mfma_f32_16x16x32_bf16 v[70:73], v[138:141], v[186:189], v[70:73]
	v_mfma_f32_16x16x32_bf16 v[70:73], v[142:145], v[190:193], v[70:73]
	v_mfma_f32_16x16x32_bf16 v[66:69], v[154:157], v[186:189], v[66:69]
	v_mfma_f32_16x16x32_bf16 v[66:69], v[158:161], v[190:193], v[66:69]
	s_barrier
	s_add_i32 s18, s67, s16
	v_lshl_add_u64 v[210:211], v[210:211], 0, s[12:13]
	s_mov_b32 m0, s18
	ds_read_b128 v[162:165], v249 offset:49152
	ds_read_b128 v[166:169], v249 offset:50176
	ds_read_b128 v[170:173], v249 offset:51200
	ds_read_b128 v[174:177], v249 offset:52224
	ds_read_b128 v[178:181], v249 offset:53248
	ds_read_b128 v[182:185], v249 offset:54272
	ds_read_b128 v[186:189], v249 offset:55296
	ds_read_b128 v[190:193], v249 offset:56320
	global_load_lds_dwordx4 v[210:211], off
	s_add_i32 m0, s18, 0x2000
	s_add_u32 s18, s26, 0x380080
	v_lshl_add_u64 v[210:211], v[212:213], 0, s[12:13]
	s_addc_u32 s19, s27, 0
	s_add_i32 s26, s68, s16
	global_load_lds_dwordx4 v[210:211], off
	v_lshl_add_u64 v[210:211], s[18:19], 0, v[196:197]
	s_mov_b32 m0, s26
	s_nop 0
	global_load_lds_dwordx4 v[210:211], off
	v_lshl_add_u64 v[210:211], s[18:19], 0, v[200:201]
	s_add_i32 m0, s26, 0x2000
	s_nop 0
	global_load_lds_dwordx4 v[210:211], off
	v_lshl_add_u64 v[210:211], v[214:215], 0, s[12:13]
	s_mov_b32 m0, s38
	s_nop 0
	global_load_lds_dwordx4 v[210:211], off
	v_lshl_add_u64 v[210:211], v[216:217], 0, s[12:13]
	s_mov_b32 m0, s39
	s_nop 0
	global_load_lds_dwordx4 v[210:211], off
	s_waitcnt vmcnt(8)
	s_waitcnt lgkmcnt(0)
	s_barrier
	s_waitcnt lgkmcnt(0)
	v_mfma_f32_16x16x32_bf16 v[62:65], v[114:117], v[162:165], v[62:65]
	v_mfma_f32_16x16x32_bf16 v[62:65], v[118:121], v[166:169], v[62:65]
	v_mfma_f32_16x16x32_bf16 v[58:61], v[126:129], v[162:165], v[58:61]
	v_mfma_f32_16x16x32_bf16 v[58:61], v[134:137], v[166:169], v[58:61]
	v_mfma_f32_16x16x32_bf16 v[46:49], v[114:117], v[170:173], v[46:49]
	v_mfma_f32_16x16x32_bf16 v[46:49], v[118:121], v[174:177], v[46:49]
	v_mfma_f32_16x16x32_bf16 v[42:45], v[126:129], v[170:173], v[42:45]
	v_mfma_f32_16x16x32_bf16 v[42:45], v[134:137], v[174:177], v[42:45]
	v_mfma_f32_16x16x32_bf16 v[30:33], v[114:117], v[178:181], v[30:33]
	v_mfma_f32_16x16x32_bf16 v[30:33], v[118:121], v[182:185], v[30:33]
	v_mfma_f32_16x16x32_bf16 v[26:29], v[126:129], v[178:181], v[26:29]
	v_mfma_f32_16x16x32_bf16 v[26:29], v[134:137], v[182:185], v[26:29]
	v_mfma_f32_16x16x32_bf16 v[14:17], v[114:117], v[186:189], v[14:17]
	v_mfma_f32_16x16x32_bf16 v[14:17], v[118:121], v[190:193], v[14:17]
	v_mfma_f32_16x16x32_bf16 v[10:13], v[126:129], v[186:189], v[10:13]
	v_mfma_f32_16x16x32_bf16 v[10:13], v[134:137], v[190:193], v[10:13]
	v_mfma_f32_16x16x32_bf16 v[54:57], v[138:141], v[162:165], v[54:57]
	v_mfma_f32_16x16x32_bf16 v[54:57], v[142:145], v[166:169], v[54:57]
	v_mfma_f32_16x16x32_bf16 v[50:53], v[154:157], v[162:165], v[50:53]
	v_mfma_f32_16x16x32_bf16 v[50:53], v[158:161], v[166:169], v[50:53]
	v_mfma_f32_16x16x32_bf16 v[38:41], v[138:141], v[170:173], v[38:41]
	v_mfma_f32_16x16x32_bf16 v[38:41], v[142:145], v[174:177], v[38:41]
	v_mfma_f32_16x16x32_bf16 v[34:37], v[154:157], v[170:173], v[34:37]
	v_mfma_f32_16x16x32_bf16 v[34:37], v[158:161], v[174:177], v[34:37]
	v_mfma_f32_16x16x32_bf16 v[22:25], v[138:141], v[178:181], v[22:25]
	v_mfma_f32_16x16x32_bf16 v[22:25], v[142:145], v[182:185], v[22:25]
	v_mfma_f32_16x16x32_bf16 v[18:21], v[154:157], v[178:181], v[18:21]
	v_mfma_f32_16x16x32_bf16 v[18:21], v[158:161], v[182:185], v[18:21]
	v_mfma_f32_16x16x32_bf16 v[6:9], v[138:141], v[186:189], v[6:9]
	v_mfma_f32_16x16x32_bf16 v[6:9], v[142:145], v[190:193], v[6:9]
	v_mfma_f32_16x16x32_bf16 v[2:5], v[154:157], v[186:189], v[2:5]
	v_mfma_f32_16x16x32_bf16 v[2:5], v[158:161], v[190:193], v[2:5]
	s_barrier
	s_add_i32 s66, s66, 2
	s_add_u32 s64, s64, 0x100
	s_addc_u32 s65, s65, 0
	s_cmpk_gt_u32 s66, 0xdd
	s_mov_b64 s[18:19], s[4:5]

.LBB0_1646:
	s_ashr_i32 s63, s62, 31
	s_lshl_b64 s[0:1], s[62:63], 21
	s_add_u32 s64, s52, s0
	s_addc_u32 s65, s53, s1
	s_and_b64 s[0:1], s[4:5], exec
	s_cselect_b32 s0, s65, s11
	s_cselect_b32 s1, s64, s10
	s_ashr_i32 s61, s60, 31
	s_lshl_b64 s[16:17], s[60:61], 21
	s_add_u32 s66, s31, s16
	s_addc_u32 s67, s35, s17
	s_and_b64 s[16:17], s[4:5], exec
	s_cselect_b32 s7, s67, s19
	s_cselect_b32 s9, s66, s18
	s_add_u32 s10, s10, 0x100080
	s_addc_u32 s11, s11, 0
	s_add_u32 s16, s18, 0x100
	s_addc_u32 s17, s19, 0
	s_mov_b32 s61, -2
	s_waitcnt lgkmcnt(0)
	ds_read_b128 v[30:33], v200
	ds_read_b128 v[38:41], v200 offset:1024
	ds_read_b128 v[42:45], v200 offset:2048
	ds_read_b128 v[50:53], v200 offset:3072
	ds_read_b128 v[164:167], v201
	ds_read_b128 v[168:171], v201 offset:1024
	ds_read_b128 v[172:175], v201 offset:2048
	ds_read_b128 v[176:179], v201 offset:3072
	s_add_u32 s18, s10, 0xfff00080
	s_addc_u32 s19, s11, -1
	s_cmp_eq_u32 s61, 60
	s_cselect_b32 s69, s0, s19
	s_cselect_b32 s68, s1, s18
	s_cselect_b32 s19, s7, s17
	s_cselect_b32 s18, s9, s16
	v_lshl_add_u64 v[222:223], s[10:11], 0, v[156:157]
	s_add_i32 m0, s39, 0xc000
	ds_read_b128 v[180:183], v202
	ds_read_b128 v[184:187], v202 offset:1024
	ds_read_b128 v[188:191], v202 offset:2048
	ds_read_b128 v[192:195], v202 offset:3072
	ds_read_b128 v[206:209], v202 offset:4096
	ds_read_b128 v[210:213], v202 offset:5120
	ds_read_b128 v[214:217], v202 offset:6144
	ds_read_b128 v[218:221], v202 offset:7168
	global_load_lds_dwordx4 v[222:223], off
	v_lshl_add_u64 v[222:223], s[10:11], 0, v[158:159]
	s_add_i32 m0, s39, 0xe000
	s_nop 0
	global_load_lds_dwordx4 v[222:223], off
	s_waitcnt vmcnt(24)
	s_cmp_lg_u32 s70, 1
	s_cbranch_scc1 .Lrlx4_0
	s_waitcnt vmcnt(8)
.Lrlx4_0:
	s_waitcnt lgkmcnt(0)
	s_barrier
	s_waitcnt lgkmcnt(0)
	v_mfma_f32_16x16x32_bf16 v[138:141], v[30:33], v[180:183], 0
	v_mfma_f32_16x16x32_bf16 v[138:141], v[38:41], v[184:187], v[138:141]
	v_mfma_f32_16x16x32_bf16 v[142:145], v[42:45], v[180:183], 0
	v_mfma_f32_16x16x32_bf16 v[142:145], v[50:53], v[184:187], v[142:145]
	v_mfma_f32_16x16x32_bf16 v[122:125], v[30:33], v[188:191], 0
	v_mfma_f32_16x16x32_bf16 v[122:125], v[38:41], v[192:195], v[122:125]
	v_mfma_f32_16x16x32_bf16 v[126:129], v[42:45], v[188:191], 0
	v_mfma_f32_16x16x32_bf16 v[126:129], v[50:53], v[192:195], v[126:129]
	v_mfma_f32_16x16x32_bf16 v[106:109], v[30:33], v[206:209], 0
	v_mfma_f32_16x16x32_bf16 v[106:109], v[38:41], v[210:213], v[106:109]
	v_mfma_f32_16x16x32_bf16 v[110:113], v[42:45], v[206:209], 0
	v_mfma_f32_16x16x32_bf16 v[110:113], v[50:53], v[210:213], v[110:113]
	v_mfma_f32_16x16x32_bf16 v[90:93], v[30:33], v[214:217], 0
	v_mfma_f32_16x16x32_bf16 v[90:93], v[38:41], v[218:221], v[90:93]
	v_mfma_f32_16x16x32_bf16 v[94:97], v[42:45], v[214:217], 0
	v_mfma_f32_16x16x32_bf16 v[94:97], v[50:53], v[218:221], v[94:97]
	v_mfma_f32_16x16x32_bf16 v[130:133], v[164:167], v[180:183], 0
	v_mfma_f32_16x16x32_bf16 v[130:133], v[168:171], v[184:187], v[130:133]
	v_mfma_f32_16x16x32_bf16 v[134:137], v[172:175], v[180:183], 0
	v_mfma_f32_16x16x32_bf16 v[134:137], v[176:179], v[184:187], v[134:137]
	v_mfma_f32_16x16x32_bf16 v[114:117], v[164:167], v[188:191], 0
	v_mfma_f32_16x16x32_bf16 v[114:117], v[168:171], v[192:195], v[114:117]
	v_mfma_f32_16x16x32_bf16 v[118:121], v[172:175], v[188:191], 0
	v_mfma_f32_16x16x32_bf16 v[118:121], v[176:179], v[192:195], v[118:121]
	v_mfma_f32_16x16x32_bf16 v[98:101], v[164:167], v[206:209], 0
	v_mfma_f32_16x16x32_bf16 v[98:101], v[168:171], v[210:213], v[98:101]
	v_mfma_f32_16x16x32_bf16 v[102:105], v[172:175], v[206:209], 0
	v_mfma_f32_16x16x32_bf16 v[102:105], v[176:179], v[210:213], v[102:105]
	v_mfma_f32_16x16x32_bf16 v[82:85], v[164:167], v[214:217], 0
	v_mfma_f32_16x16x32_bf16 v[82:85], v[168:171], v[218:221], v[82:85]
	v_mfma_f32_16x16x32_bf16 v[86:89], v[172:175], v[214:217], 0
	v_mfma_f32_16x16x32_bf16 v[86:89], v[176:179], v[218:221], v[86:89]
	s_barrier
	s_add_i32 s63, s77, s37
	v_lshl_add_u64 v[222:223], s[18:19], 0, v[148:149]
	s_mov_b32 m0, s63
	ds_read_b128 v[180:183], v202 offset:16384
	ds_read_b128 v[184:187], v202 offset:17408
	ds_read_b128 v[188:191], v202 offset:18432
	ds_read_b128 v[192:195], v202 offset:19456
	ds_read_b128 v[206:209], v202 offset:20480
	ds_read_b128 v[210:213], v202 offset:21504
	ds_read_b128 v[214:217], v202 offset:22528
	ds_read_b128 v[218:221], v202 offset:23552
	global_load_lds_dwordx4 v[222:223], off
	s_add_i32 m0, s63, 0x2000
	s_add_u32 s82, s18, 0x100000
	v_lshl_add_u64 v[224:225], s[18:19], 0, v[152:153]
	s_addc_u32 s83, s19, 0
	s_add_i32 s63, s78, s37
	global_load_lds_dwordx4 v[224:225], off
	v_lshl_add_u64 v[226:227], s[82:83], 0, v[148:149]
	s_mov_b32 m0, s63
	v_lshl_add_u64 v[228:229], s[68:69], 0, v[150:151]
	global_load_lds_dwordx4 v[226:227], off
	v_lshl_add_u64 v[226:227], s[82:83], 0, v[152:153]
	s_add_i32 m0, s63, 0x2000
	s_nop 0
	global_load_lds_dwordx4 v[226:227], off
	v_lshl_add_u64 v[226:227], s[68:69], 0, v[146:147]
	s_mov_b32 m0, s39
	s_nop 0
	global_load_lds_dwordx4 v[226:227], off
	s_mov_b32 m0, s41
	s_nop 0
	global_load_lds_dwordx4 v[228:229], off
	s_waitcnt vmcnt(24)
	s_cmp_lg_u32 s70, 1
	s_cbranch_scc1 .Lrlx4_1
	s_waitcnt vmcnt(8)
.Lrlx4_1:
	s_waitcnt lgkmcnt(0)
	s_barrier
	s_waitcnt lgkmcnt(0)
	v_mfma_f32_16x16x32_bf16 v[74:77], v[30:33], v[180:183], 0
	v_mfma_f32_16x16x32_bf16 v[74:77], v[38:41], v[184:187], v[74:77]
	v_mfma_f32_16x16x32_bf16 v[78:81], v[42:45], v[180:183], 0
	v_mfma_f32_16x16x32_bf16 v[78:81], v[50:53], v[184:187], v[78:81]
	v_mfma_f32_16x16x32_bf16 v[58:61], v[30:33], v[188:191], 0
	v_mfma_f32_16x16x32_bf16 v[58:61], v[38:41], v[192:195], v[58:61]
	v_mfma_f32_16x16x32_bf16 v[62:65], v[42:45], v[188:191], 0
	v_mfma_f32_16x16x32_bf16 v[62:65], v[50:53], v[192:195], v[62:65]
	v_mfma_f32_16x16x32_bf16 v[26:29], v[30:33], v[206:209], 0
	v_mfma_f32_16x16x32_bf16 v[26:29], v[38:41], v[210:213], v[26:29]
	v_mfma_f32_16x16x32_bf16 v[34:37], v[42:45], v[206:209], 0
	v_mfma_f32_16x16x32_bf16 v[34:37], v[50:53], v[210:213], v[34:37]
	v_mfma_f32_16x16x32_bf16 v[10:13], v[30:33], v[214:217], 0
	v_mfma_f32_16x16x32_bf16 v[10:13], v[38:41], v[218:221], v[10:13]
	v_mfma_f32_16x16x32_bf16 v[14:17], v[42:45], v[214:217], 0
	v_mfma_f32_16x16x32_bf16 v[14:17], v[50:53], v[218:221], v[14:17]
	v_mfma_f32_16x16x32_bf16 v[18:21], v[164:167], v[206:209], 0
	v_mfma_f32_16x16x32_bf16 v[18:21], v[168:171], v[210:213], v[18:21]
	v_mfma_f32_16x16x32_bf16 v[22:25], v[172:175], v[206:209], 0
	v_mfma_f32_16x16x32_bf16 v[22:25], v[176:179], v[210:213], v[22:25]
	v_mfma_f32_16x16x32_bf16 v[2:5], v[164:167], v[214:217], 0
	v_mfma_f32_16x16x32_bf16 v[2:5], v[168:171], v[218:221], v[2:5]
	v_mfma_f32_16x16x32_bf16 v[6:9], v[172:175], v[214:217], 0
	v_mfma_f32_16x16x32_bf16 v[6:9], v[176:179], v[218:221], v[6:9]
	v_mfma_f32_16x16x32_bf16 v[30:33], v[164:167], v[180:183], 0
	v_mfma_f32_16x16x32_bf16 v[30:33], v[168:171], v[184:187], v[30:33]
	v_mfma_f32_16x16x32_bf16 v[38:41], v[172:175], v[180:183], 0
	v_mfma_f32_16x16x32_bf16 v[38:41], v[176:179], v[184:187], v[38:41]
	v_mfma_f32_16x16x32_bf16 v[42:45], v[164:167], v[188:191], 0
	v_mfma_f32_16x16x32_bf16 v[42:45], v[168:171], v[192:195], v[42:45]
	v_mfma_f32_16x16x32_bf16 v[46:49], v[172:175], v[188:191], 0
	v_mfma_f32_16x16x32_bf16 v[50:53], v[176:179], v[192:195], v[46:49]
	s_barrier
	s_add_i32 s63, 0, 0x18000
	s_add_i32 s82, 0, 0x1c000
	v_add_u32_e32 v70, s63, v196
	v_add_u32_e32 v155, s82, v196
	ds_read_b128 v[46:49], v70
	ds_read_b128 v[54:57], v70 offset:1024
	ds_read_b128 v[66:69], v70 offset:2048
	ds_read_b128 v[70:73], v70 offset:3072
	ds_read_b128 v[164:167], v155
	ds_read_b128 v[168:171], v155 offset:1024
	ds_read_b128 v[172:175], v155 offset:2048
	ds_read_b128 v[176:179], v155 offset:3072
	s_add_u32 s68, s68, 0x100000
	s_addc_u32 s69, s69, 0
	s_mov_b32 m0, s43
	v_lshl_add_u64 v[230:231], s[68:69], 0, v[146:147]
	ds_read_b128 v[180:183], v202 offset:32768
	ds_read_b128 v[184:187], v202 offset:33792
	ds_read_b128 v[188:191], v202 offset:34816
	ds_read_b128 v[192:195], v202 offset:35840
	ds_read_b128 v[206:209], v202 offset:36864
	ds_read_b128 v[210:213], v202 offset:37888
	ds_read_b128 v[214:217], v202 offset:38912
	ds_read_b128 v[218:221], v202 offset:39936
	global_load_lds_dwordx4 v[230:231], off
	v_lshl_add_u64 v[230:231], s[68:69], 0, v[150:151]
	s_mov_b32 m0, s57
	s_nop 0
	global_load_lds_dwordx4 v[230:231], off
	s_waitcnt vmcnt(8)
	s_waitcnt lgkmcnt(0)
	s_barrier
	s_waitcnt lgkmcnt(0)
	v_mfma_f32_16x16x32_bf16 v[138:141], v[46:49], v[180:183], v[138:141]
	v_mfma_f32_16x16x32_bf16 v[138:141], v[54:57], v[184:187], v[138:141]
	v_mfma_f32_16x16x32_bf16 v[142:145], v[66:69], v[180:183], v[142:145]
	v_mfma_f32_16x16x32_bf16 v[142:145], v[70:73], v[184:187], v[142:145]
	v_mfma_f32_16x16x32_bf16 v[122:125], v[46:49], v[188:191], v[122:125]
	v_mfma_f32_16x16x32_bf16 v[122:125], v[54:57], v[192:195], v[122:125]
	v_mfma_f32_16x16x32_bf16 v[126:129], v[66:69], v[188:191], v[126:129]
	v_mfma_f32_16x16x32_bf16 v[126:129], v[70:73], v[192:195], v[126:129]
	v_mfma_f32_16x16x32_bf16 v[106:109], v[46:49], v[206:209], v[106:109]
	v_mfma_f32_16x16x32_bf16 v[106:109], v[54:57], v[210:213], v[106:109]
	v_mfma_f32_16x16x32_bf16 v[110:113], v[66:69], v[206:209], v[110:113]
	v_mfma_f32_16x16x32_bf16 v[110:113], v[70:73], v[210:213], v[110:113]
	v_mfma_f32_16x16x32_bf16 v[90:93], v[46:49], v[214:217], v[90:93]
	v_mfma_f32_16x16x32_bf16 v[90:93], v[54:57], v[218:221], v[90:93]
	v_mfma_f32_16x16x32_bf16 v[94:97], v[66:69], v[214:217], v[94:97]
	v_mfma_f32_16x16x32_bf16 v[94:97], v[70:73], v[218:221], v[94:97]
	v_mfma_f32_16x16x32_bf16 v[130:133], v[164:167], v[180:183], v[130:133]
	v_mfma_f32_16x16x32_bf16 v[130:133], v[168:171], v[184:187], v[130:133]
	v_mfma_f32_16x16x32_bf16 v[134:137], v[172:175], v[180:183], v[134:137]
	v_mfma_f32_16x16x32_bf16 v[134:137], v[176:179], v[184:187], v[134:137]
	v_mfma_f32_16x16x32_bf16 v[114:117], v[164:167], v[188:191], v[114:117]
	v_mfma_f32_16x16x32_bf16 v[114:117], v[168:171], v[192:195], v[114:117]
	v_mfma_f32_16x16x32_bf16 v[118:121], v[172:175], v[188:191], v[118:121]
	v_mfma_f32_16x16x32_bf16 v[118:121], v[176:179], v[192:195], v[118:121]
	v_mfma_f32_16x16x32_bf16 v[98:101], v[164:167], v[206:209], v[98:101]
	v_mfma_f32_16x16x32_bf16 v[98:101], v[168:171], v[210:213], v[98:101]
	v_mfma_f32_16x16x32_bf16 v[102:105], v[172:175], v[206:209], v[102:105]
	v_mfma_f32_16x16x32_bf16 v[102:105], v[176:179], v[210:213], v[102:105]
	v_mfma_f32_16x16x32_bf16 v[82:85], v[164:167], v[214:217], v[82:85]
	v_mfma_f32_16x16x32_bf16 v[82:85], v[168:171], v[218:221], v[82:85]
	v_mfma_f32_16x16x32_bf16 v[86:89], v[172:175], v[214:217], v[86:89]
	v_mfma_f32_16x16x32_bf16 v[86:89], v[176:179], v[218:221], v[86:89]
	s_barrier
	s_add_i32 s63, s63, s37
	v_lshl_add_u64 v[222:223], v[222:223], 0, s[26:27]
	s_mov_b32 m0, s63
	ds_read_b128 v[180:183], v202 offset:49152
	ds_read_b128 v[184:187], v202 offset:50176
	ds_read_b128 v[188:191], v202 offset:51200
	ds_read_b128 v[192:195], v202 offset:52224
	ds_read_b128 v[206:209], v202 offset:53248
	ds_read_b128 v[210:213], v202 offset:54272
	ds_read_b128 v[214:217], v202 offset:55296
	ds_read_b128 v[218:221], v202 offset:56320
	global_load_lds_dwordx4 v[222:223], off
	s_add_i32 m0, s63, 0x2000
	s_add_u32 s18, s18, 0x100080
	v_lshl_add_u64 v[222:223], v[224:225], 0, s[26:27]
	s_addc_u32 s19, s19, 0
	s_add_i32 s63, s82, s37
	global_load_lds_dwordx4 v[222:223], off
	v_lshl_add_u64 v[222:223], s[18:19], 0, v[148:149]
	s_mov_b32 m0, s63
	s_nop 0
	global_load_lds_dwordx4 v[222:223], off
	v_lshl_add_u64 v[222:223], s[18:19], 0, v[152:153]
	s_add_i32 m0, s63, 0x2000
	s_nop 0
	global_load_lds_dwordx4 v[222:223], off
	v_lshl_add_u64 v[222:223], v[226:227], 0, s[26:27]
	s_mov_b32 m0, s71
	s_nop 0
	global_load_lds_dwordx4 v[222:223], off
	v_lshl_add_u64 v[222:223], v[228:229], 0, s[26:27]
	s_mov_b32 m0, s72
	s_nop 0
	global_load_lds_dwordx4 v[222:223], off
	s_waitcnt vmcnt(8)
	s_waitcnt lgkmcnt(0)
	s_barrier
	s_waitcnt lgkmcnt(0)
	v_mfma_f32_16x16x32_bf16 v[74:77], v[46:49], v[180:183], v[74:77]
	v_mfma_f32_16x16x32_bf16 v[74:77], v[54:57], v[184:187], v[74:77]
	v_mfma_f32_16x16x32_bf16 v[78:81], v[66:69], v[180:183], v[78:81]
	v_mfma_f32_16x16x32_bf16 v[78:81], v[70:73], v[184:187], v[78:81]
	v_mfma_f32_16x16x32_bf16 v[58:61], v[46:49], v[188:191], v[58:61]
	v_mfma_f32_16x16x32_bf16 v[58:61], v[54:57], v[192:195], v[58:61]
	v_mfma_f32_16x16x32_bf16 v[62:65], v[66:69], v[188:191], v[62:65]
	v_mfma_f32_16x16x32_bf16 v[62:65], v[70:73], v[192:195], v[62:65]
	v_mfma_f32_16x16x32_bf16 v[26:29], v[46:49], v[206:209], v[26:29]
	v_mfma_f32_16x16x32_bf16 v[26:29], v[54:57], v[210:213], v[26:29]
	v_mfma_f32_16x16x32_bf16 v[34:37], v[66:69], v[206:209], v[34:37]
	v_mfma_f32_16x16x32_bf16 v[34:37], v[70:73], v[210:213], v[34:37]
	v_mfma_f32_16x16x32_bf16 v[10:13], v[46:49], v[214:217], v[10:13]
	v_mfma_f32_16x16x32_bf16 v[10:13], v[54:57], v[218:221], v[10:13]
	v_mfma_f32_16x16x32_bf16 v[14:17], v[66:69], v[214:217], v[14:17]
	v_mfma_f32_16x16x32_bf16 v[14:17], v[70:73], v[218:221], v[14:17]
	v_mfma_f32_16x16x32_bf16 v[30:33], v[164:167], v[180:183], v[30:33]
	v_mfma_f32_16x16x32_bf16 v[66:69], v[168:171], v[184:187], v[30:33]
	v_mfma_f32_16x16x32_bf16 v[30:33], v[172:175], v[180:183], v[38:41]
	v_mfma_f32_16x16x32_bf16 v[70:73], v[176:179], v[184:187], v[30:33]
	v_mfma_f32_16x16x32_bf16 v[30:33], v[164:167], v[188:191], v[42:45]
	v_mfma_f32_16x16x32_bf16 v[46:49], v[168:171], v[192:195], v[30:33]
	v_mfma_f32_16x16x32_bf16 v[30:33], v[172:175], v[188:191], v[50:53]
	v_mfma_f32_16x16x32_bf16 v[54:57], v[176:179], v[192:195], v[30:33]
	v_mfma_f32_16x16x32_bf16 v[18:21], v[164:167], v[206:209], v[18:21]
	v_mfma_f32_16x16x32_bf16 v[18:21], v[168:171], v[210:213], v[18:21]
	v_mfma_f32_16x16x32_bf16 v[22:25], v[172:175], v[206:209], v[22:25]
	v_mfma_f32_16x16x32_bf16 v[22:25], v[176:179], v[210:213], v[22:25]
	v_mfma_f32_16x16x32_bf16 v[2:5], v[164:167], v[214:217], v[2:5]
	v_mfma_f32_16x16x32_bf16 v[2:5], v[168:171], v[218:221], v[2:5]
	v_mfma_f32_16x16x32_bf16 v[6:9], v[172:175], v[214:217], v[6:9]
	v_mfma_f32_16x16x32_bf16 v[6:9], v[176:179], v[218:221], v[6:9]
	s_barrier
	s_add_i32 s61, s61, 2
	s_add_u32 s10, s10, 0x100
	s_addc_u32 s11, s11, 0
	s_add_u32 s16, s16, 0x100
	s_addc_u32 s17, s17, 0
	s_cmp_gt_u32 s61, 61

.LBB0_1920:
	s_ashr_i32 s31, s30, 31
	s_lshl_b64 s[34:35], s[30:31], 21
	s_add_u32 s34, s54, s34
	s_addc_u32 s35, s55, s35
	s_and_b64 s[36:37], s[2:3], exec
	s_cselect_b32 s31, s35, s39
	s_cselect_b32 s69, s34, s38
	s_ashr_i32 s29, s28, 31
	s_lshl_b64 s[36:37], s[28:29], 21
	s_add_u32 s36, s1, s36
	s_addc_u32 s37, s16, s37
	s_and_b64 s[42:43], s[2:3], exec
	s_cselect_b32 s29, s37, s41
	s_cselect_b32 s70, s36, s40
	s_add_u32 s38, s38, 0x100080
	s_addc_u32 s39, s39, 0
	s_add_u32 s71, s40, 0x100
	s_addc_u32 s72, s41, 0
	s_mov_b32 s73, -2
	ds_read_b128 v[130:133], v212
	ds_read_b128 v[134:137], v212 offset:1024
	ds_read_b128 v[138:141], v212 offset:2048
	ds_read_b128 v[142:145], v212 offset:3072
	ds_read_b128 v[146:149], v213
	ds_read_b128 v[150:153], v213 offset:1024
	ds_read_b128 v[154:157], v213 offset:2048
	ds_read_b128 v[158:161], v213 offset:3072
	s_add_u32 s40, s38, 0xfff00080
	s_addc_u32 s41, s39, -1
	s_cmp_eq_u32 s73, 60
	s_cselect_b32 s43, s31, s41
	s_cselect_b32 s42, s69, s40
	s_cselect_b32 s41, s29, s72
	s_cselect_b32 s40, s70, s71
	v_lshl_add_u64 v[216:217], s[38:39], 0, v[178:179]
	s_add_i32 m0, s19, 0xc000
	ds_read_b128 v[162:165], v214
	ds_read_b128 v[166:169], v214 offset:1024
	ds_read_b128 v[186:189], v214 offset:2048
	ds_read_b128 v[190:193], v214 offset:3072
	ds_read_b128 v[194:197], v214 offset:4096
	ds_read_b128 v[198:201], v214 offset:5120
	ds_read_b128 v[202:205], v214 offset:6144
	ds_read_b128 v[206:209], v214 offset:7168
	global_load_lds_dwordx4 v[216:217], off
	v_lshl_add_u64 v[216:217], s[38:39], 0, v[180:181]
	s_add_i32 m0, s19, 0xe000
	s_nop 0
	global_load_lds_dwordx4 v[216:217], off
	s_waitcnt vmcnt(24)
	s_cmp_lg_u32 s47, 1
	s_cbranch_scc1 .Lrlx5_0
	s_waitcnt vmcnt(8)
.Lrlx5_0:
	s_waitcnt lgkmcnt(0)
	s_barrier
	s_waitcnt lgkmcnt(0)
	v_mfma_f32_16x16x32_bf16 v[126:129], v[130:133], v[162:165], 0
	v_mfma_f32_16x16x32_bf16 v[126:129], v[134:137], v[166:169], v[126:129]
	v_mfma_f32_16x16x32_bf16 v[122:125], v[138:141], v[162:165], 0
	v_mfma_f32_16x16x32_bf16 v[122:125], v[142:145], v[166:169], v[122:125]
	v_mfma_f32_16x16x32_bf16 v[110:113], v[130:133], v[186:189], 0
	v_mfma_f32_16x16x32_bf16 v[110:113], v[134:137], v[190:193], v[110:113]
	v_mfma_f32_16x16x32_bf16 v[106:109], v[138:141], v[186:189], 0
	v_mfma_f32_16x16x32_bf16 v[106:109], v[142:145], v[190:193], v[106:109]
	v_mfma_f32_16x16x32_bf16 v[94:97], v[130:133], v[194:197], 0
	v_mfma_f32_16x16x32_bf16 v[94:97], v[134:137], v[198:201], v[94:97]
	v_mfma_f32_16x16x32_bf16 v[90:93], v[138:141], v[194:197], 0
	v_mfma_f32_16x16x32_bf16 v[90:93], v[142:145], v[198:201], v[90:93]
	v_mfma_f32_16x16x32_bf16 v[78:81], v[130:133], v[202:205], 0
	v_mfma_f32_16x16x32_bf16 v[78:81], v[134:137], v[206:209], v[78:81]
	v_mfma_f32_16x16x32_bf16 v[74:77], v[138:141], v[202:205], 0
	v_mfma_f32_16x16x32_bf16 v[74:77], v[142:145], v[206:209], v[74:77]
	v_mfma_f32_16x16x32_bf16 v[118:121], v[146:149], v[162:165], 0
	v_mfma_f32_16x16x32_bf16 v[118:121], v[150:153], v[166:169], v[118:121]
	v_mfma_f32_16x16x32_bf16 v[114:117], v[154:157], v[162:165], 0
	v_mfma_f32_16x16x32_bf16 v[114:117], v[158:161], v[166:169], v[114:117]
	v_mfma_f32_16x16x32_bf16 v[102:105], v[146:149], v[186:189], 0
	v_mfma_f32_16x16x32_bf16 v[102:105], v[150:153], v[190:193], v[102:105]
	v_mfma_f32_16x16x32_bf16 v[98:101], v[154:157], v[186:189], 0
	v_mfma_f32_16x16x32_bf16 v[98:101], v[158:161], v[190:193], v[98:101]
	v_mfma_f32_16x16x32_bf16 v[86:89], v[146:149], v[194:197], 0
	v_mfma_f32_16x16x32_bf16 v[86:89], v[150:153], v[198:201], v[86:89]
	v_mfma_f32_16x16x32_bf16 v[82:85], v[154:157], v[194:197], 0
	v_mfma_f32_16x16x32_bf16 v[82:85], v[158:161], v[198:201], v[82:85]
	v_mfma_f32_16x16x32_bf16 v[70:73], v[146:149], v[202:205], 0
	v_mfma_f32_16x16x32_bf16 v[70:73], v[150:153], v[206:209], v[70:73]
	v_mfma_f32_16x16x32_bf16 v[66:69], v[154:157], v[202:205], 0
	v_mfma_f32_16x16x32_bf16 v[66:69], v[158:161], v[206:209], v[66:69]
	s_barrier
	s_add_i32 s76, s57, s17
	v_lshl_add_u64 v[216:217], s[40:41], 0, v[172:173]
	s_mov_b32 m0, s76
	ds_read_b128 v[162:165], v214 offset:16384
	ds_read_b128 v[166:169], v214 offset:17408
	ds_read_b128 v[186:189], v214 offset:18432
	ds_read_b128 v[190:193], v214 offset:19456
	ds_read_b128 v[194:197], v214 offset:20480
	ds_read_b128 v[198:201], v214 offset:21504
	ds_read_b128 v[202:205], v214 offset:22528
	ds_read_b128 v[206:209], v214 offset:23552
	global_load_lds_dwordx4 v[216:217], off
	s_add_i32 m0, s76, 0x2000
	s_add_u32 s76, s40, 0x100000
	v_lshl_add_u64 v[218:219], s[40:41], 0, v[176:177]
	s_addc_u32 s77, s41, 0
	s_add_i32 s78, s60, s17
	global_load_lds_dwordx4 v[218:219], off
	v_lshl_add_u64 v[220:221], s[76:77], 0, v[172:173]
	s_mov_b32 m0, s78
	v_lshl_add_u64 v[222:223], s[42:43], 0, v[174:175]
	global_load_lds_dwordx4 v[220:221], off
	v_lshl_add_u64 v[220:221], s[76:77], 0, v[176:177]
	s_add_i32 m0, s78, 0x2000
	s_nop 0
	global_load_lds_dwordx4 v[220:221], off
	v_lshl_add_u64 v[220:221], s[42:43], 0, v[170:171]
	s_mov_b32 m0, s19
	s_nop 0
	global_load_lds_dwordx4 v[220:221], off
	s_mov_b32 m0, s44
	s_nop 0
	global_load_lds_dwordx4 v[222:223], off
	s_waitcnt vmcnt(24)
	s_cmp_lg_u32 s47, 1
	s_cbranch_scc1 .Lrlx5_1
	s_waitcnt vmcnt(8)
.Lrlx5_1:
	s_waitcnt lgkmcnt(0)
	s_barrier
	s_waitcnt lgkmcnt(0)
	v_mfma_f32_16x16x32_bf16 v[62:65], v[130:133], v[162:165], 0
	v_mfma_f32_16x16x32_bf16 v[62:65], v[134:137], v[166:169], v[62:65]
	v_mfma_f32_16x16x32_bf16 v[58:61], v[138:141], v[162:165], 0
	v_mfma_f32_16x16x32_bf16 v[58:61], v[142:145], v[166:169], v[58:61]
	v_mfma_f32_16x16x32_bf16 v[46:49], v[130:133], v[186:189], 0
	v_mfma_f32_16x16x32_bf16 v[46:49], v[134:137], v[190:193], v[46:49]
	v_mfma_f32_16x16x32_bf16 v[42:45], v[138:141], v[186:189], 0
	v_mfma_f32_16x16x32_bf16 v[42:45], v[142:145], v[190:193], v[42:45]
	v_mfma_f32_16x16x32_bf16 v[30:33], v[130:133], v[194:197], 0
	v_mfma_f32_16x16x32_bf16 v[30:33], v[134:137], v[198:201], v[30:33]
	v_mfma_f32_16x16x32_bf16 v[26:29], v[138:141], v[194:197], 0
	v_mfma_f32_16x16x32_bf16 v[26:29], v[142:145], v[198:201], v[26:29]
	v_mfma_f32_16x16x32_bf16 v[14:17], v[130:133], v[202:205], 0
	v_mfma_f32_16x16x32_bf16 v[14:17], v[134:137], v[206:209], v[14:17]
	v_mfma_f32_16x16x32_bf16 v[10:13], v[138:141], v[202:205], 0
	v_mfma_f32_16x16x32_bf16 v[10:13], v[142:145], v[206:209], v[10:13]
	v_mfma_f32_16x16x32_bf16 v[54:57], v[146:149], v[162:165], 0
	v_mfma_f32_16x16x32_bf16 v[54:57], v[150:153], v[166:169], v[54:57]
	v_mfma_f32_16x16x32_bf16 v[50:53], v[154:157], v[162:165], 0
	v_mfma_f32_16x16x32_bf16 v[50:53], v[158:161], v[166:169], v[50:53]
	v_mfma_f32_16x16x32_bf16 v[38:41], v[146:149], v[186:189], 0
	v_mfma_f32_16x16x32_bf16 v[38:41], v[150:153], v[190:193], v[38:41]
	v_mfma_f32_16x16x32_bf16 v[34:37], v[154:157], v[186:189], 0
	v_mfma_f32_16x16x32_bf16 v[34:37], v[158:161], v[190:193], v[34:37]
	v_mfma_f32_16x16x32_bf16 v[22:25], v[146:149], v[194:197], 0
	v_mfma_f32_16x16x32_bf16 v[22:25], v[150:153], v[198:201], v[22:25]
	v_mfma_f32_16x16x32_bf16 v[18:21], v[154:157], v[194:197], 0
	v_mfma_f32_16x16x32_bf16 v[18:21], v[158:161], v[198:201], v[18:21]
	v_mfma_f32_16x16x32_bf16 v[6:9], v[146:149], v[202:205], 0
	v_mfma_f32_16x16x32_bf16 v[6:9], v[150:153], v[206:209], v[6:9]
	v_mfma_f32_16x16x32_bf16 v[2:5], v[154:157], v[202:205], 0
	v_mfma_f32_16x16x32_bf16 v[2:5], v[158:161], v[206:209], v[2:5]
	s_barrier
	s_add_i32 s76, 0, 0x18000
	s_add_i32 s77, 0, 0x1c000
	v_add_u32_e32 v142, s76, v211
	v_add_u32_e32 v158, s77, v211
	ds_read_b128 v[130:133], v142
	ds_read_b128 v[134:137], v142 offset:1024
	ds_read_b128 v[138:141], v142 offset:2048
	ds_read_b128 v[142:145], v142 offset:3072
	ds_read_b128 v[146:149], v158
	ds_read_b128 v[150:153], v158 offset:1024
	ds_read_b128 v[154:157], v158 offset:2048
	ds_read_b128 v[158:161], v158 offset:3072
	s_add_u32 s42, s42, 0x100000
	s_addc_u32 s43, s43, 0
	s_mov_b32 m0, s45
	v_lshl_add_u64 v[224:225], s[42:43], 0, v[170:171]
	ds_read_b128 v[162:165], v214 offset:32768
	ds_read_b128 v[166:169], v214 offset:33792
	ds_read_b128 v[186:189], v214 offset:34816
	ds_read_b128 v[190:193], v214 offset:35840
	ds_read_b128 v[194:197], v214 offset:36864
	ds_read_b128 v[198:201], v214 offset:37888
	ds_read_b128 v[202:205], v214 offset:38912
	ds_read_b128 v[206:209], v214 offset:39936
	global_load_lds_dwordx4 v[224:225], off
	v_lshl_add_u64 v[224:225], s[42:43], 0, v[174:175]
	s_mov_b32 m0, s46
	s_nop 0
	global_load_lds_dwordx4 v[224:225], off
	s_waitcnt vmcnt(8)
	s_waitcnt lgkmcnt(0)
	s_barrier
	s_waitcnt lgkmcnt(0)
	v_mfma_f32_16x16x32_bf16 v[126:129], v[130:133], v[162:165], v[126:129]
	v_mfma_f32_16x16x32_bf16 v[126:129], v[134:137], v[166:169], v[126:129]
	v_mfma_f32_16x16x32_bf16 v[122:125], v[138:141], v[162:165], v[122:125]
	v_mfma_f32_16x16x32_bf16 v[122:125], v[142:145], v[166:169], v[122:125]
	v_mfma_f32_16x16x32_bf16 v[110:113], v[130:133], v[186:189], v[110:113]
	v_mfma_f32_16x16x32_bf16 v[110:113], v[134:137], v[190:193], v[110:113]
	v_mfma_f32_16x16x32_bf16 v[106:109], v[138:141], v[186:189], v[106:109]
	v_mfma_f32_16x16x32_bf16 v[106:109], v[142:145], v[190:193], v[106:109]
	v_mfma_f32_16x16x32_bf16 v[94:97], v[130:133], v[194:197], v[94:97]
	v_mfma_f32_16x16x32_bf16 v[94:97], v[134:137], v[198:201], v[94:97]
	v_mfma_f32_16x16x32_bf16 v[90:93], v[138:141], v[194:197], v[90:93]
	v_mfma_f32_16x16x32_bf16 v[90:93], v[142:145], v[198:201], v[90:93]
	v_mfma_f32_16x16x32_bf16 v[78:81], v[130:133], v[202:205], v[78:81]
	v_mfma_f32_16x16x32_bf16 v[78:81], v[134:137], v[206:209], v[78:81]
	v_mfma_f32_16x16x32_bf16 v[74:77], v[138:141], v[202:205], v[74:77]
	v_mfma_f32_16x16x32_bf16 v[74:77], v[142:145], v[206:209], v[74:77]
	v_mfma_f32_16x16x32_bf16 v[118:121], v[146:149], v[162:165], v[118:121]
	v_mfma_f32_16x16x32_bf16 v[118:121], v[150:153], v[166:169], v[118:121]
	v_mfma_f32_16x16x32_bf16 v[114:117], v[154:157], v[162:165], v[114:117]
	v_mfma_f32_16x16x32_bf16 v[114:117], v[158:161], v[166:169], v[114:117]
	v_mfma_f32_16x16x32_bf16 v[102:105], v[146:149], v[186:189], v[102:105]
	v_mfma_f32_16x16x32_bf16 v[102:105], v[150:153], v[190:193], v[102:105]
	v_mfma_f32_16x16x32_bf16 v[98:101], v[154:157], v[186:189], v[98:101]
	v_mfma_f32_16x16x32_bf16 v[98:101], v[158:161], v[190:193], v[98:101]
	v_mfma_f32_16x16x32_bf16 v[86:89], v[146:149], v[194:197], v[86:89]
	v_mfma_f32_16x16x32_bf16 v[86:89], v[150:153], v[198:201], v[86:89]
	v_mfma_f32_16x16x32_bf16 v[82:85], v[154:157], v[194:197], v[82:85]
	v_mfma_f32_16x16x32_bf16 v[82:85], v[158:161], v[198:201], v[82:85]
	v_mfma_f32_16x16x32_bf16 v[70:73], v[146:149], v[202:205], v[70:73]
	v_mfma_f32_16x16x32_bf16 v[70:73], v[150:153], v[206:209], v[70:73]
	v_mfma_f32_16x16x32_bf16 v[66:69], v[154:157], v[202:205], v[66:69]
	v_mfma_f32_16x16x32_bf16 v[66:69], v[158:161], v[206:209], v[66:69]
	s_barrier
	s_add_i32 s42, s76, s17
	v_lshl_add_u64 v[216:217], v[216:217], 0, s[8:9]
	s_mov_b32 m0, s42
	ds_read_b128 v[162:165], v214 offset:49152
	ds_read_b128 v[166:169], v214 offset:50176
	ds_read_b128 v[186:189], v214 offset:51200
	ds_read_b128 v[190:193], v214 offset:52224
	ds_read_b128 v[194:197], v214 offset:53248
	ds_read_b128 v[198:201], v214 offset:54272
	ds_read_b128 v[202:205], v214 offset:55296
	ds_read_b128 v[206:209], v214 offset:56320
	global_load_lds_dwordx4 v[216:217], off
	s_add_i32 m0, s42, 0x2000
	s_add_u32 s40, s40, 0x100080
	v_lshl_add_u64 v[216:217], v[218:219], 0, s[8:9]
	s_addc_u32 s41, s41, 0
	s_add_i32 s42, s77, s17
	global_load_lds_dwordx4 v[216:217], off
	v_lshl_add_u64 v[216:217], s[40:41], 0, v[172:173]
	s_mov_b32 m0, s42
	s_nop 0
	global_load_lds_dwordx4 v[216:217], off
	v_lshl_add_u64 v[216:217], s[40:41], 0, v[176:177]
	s_add_i32 m0, s42, 0x2000
	s_nop 0
	global_load_lds_dwordx4 v[216:217], off
	v_lshl_add_u64 v[216:217], v[220:221], 0, s[8:9]
	s_mov_b32 m0, s50
	s_nop 0
	global_load_lds_dwordx4 v[216:217], off
	v_lshl_add_u64 v[216:217], v[222:223], 0, s[8:9]
	s_mov_b32 m0, s51
	s_nop 0
	global_load_lds_dwordx4 v[216:217], off
	s_waitcnt vmcnt(8)
	s_waitcnt lgkmcnt(0)
	s_barrier
	s_waitcnt lgkmcnt(0)
	v_mfma_f32_16x16x32_bf16 v[62:65], v[130:133], v[162:165], v[62:65]
	v_mfma_f32_16x16x32_bf16 v[62:65], v[134:137], v[166:169], v[62:65]
	v_mfma_f32_16x16x32_bf16 v[58:61], v[138:141], v[162:165], v[58:61]
	v_mfma_f32_16x16x32_bf16 v[58:61], v[142:145], v[166:169], v[58:61]
	v_mfma_f32_16x16x32_bf16 v[46:49], v[130:133], v[186:189], v[46:49]
	v_mfma_f32_16x16x32_bf16 v[46:49], v[134:137], v[190:193], v[46:49]
	v_mfma_f32_16x16x32_bf16 v[42:45], v[138:141], v[186:189], v[42:45]
	v_mfma_f32_16x16x32_bf16 v[42:45], v[142:145], v[190:193], v[42:45]
	v_mfma_f32_16x16x32_bf16 v[30:33], v[130:133], v[194:197], v[30:33]
	v_mfma_f32_16x16x32_bf16 v[30:33], v[134:137], v[198:201], v[30:33]
	v_mfma_f32_16x16x32_bf16 v[26:29], v[138:141], v[194:197], v[26:29]
	v_mfma_f32_16x16x32_bf16 v[26:29], v[142:145], v[198:201], v[26:29]
	v_mfma_f32_16x16x32_bf16 v[14:17], v[130:133], v[202:205], v[14:17]
	v_mfma_f32_16x16x32_bf16 v[14:17], v[134:137], v[206:209], v[14:17]
	v_mfma_f32_16x16x32_bf16 v[10:13], v[138:141], v[202:205], v[10:13]
	v_mfma_f32_16x16x32_bf16 v[10:13], v[142:145], v[206:209], v[10:13]
	v_mfma_f32_16x16x32_bf16 v[54:57], v[146:149], v[162:165], v[54:57]
	v_mfma_f32_16x16x32_bf16 v[54:57], v[150:153], v[166:169], v[54:57]
	v_mfma_f32_16x16x32_bf16 v[50:53], v[154:157], v[162:165], v[50:53]
	v_mfma_f32_16x16x32_bf16 v[50:53], v[158:161], v[166:169], v[50:53]
	v_mfma_f32_16x16x32_bf16 v[38:41], v[146:149], v[186:189], v[38:41]
	v_mfma_f32_16x16x32_bf16 v[38:41], v[150:153], v[190:193], v[38:41]
	v_mfma_f32_16x16x32_bf16 v[34:37], v[154:157], v[186:189], v[34:37]
	v_mfma_f32_16x16x32_bf16 v[34:37], v[158:161], v[190:193], v[34:37]
	v_mfma_f32_16x16x32_bf16 v[22:25], v[146:149], v[194:197], v[22:25]
	v_mfma_f32_16x16x32_bf16 v[22:25], v[150:153], v[198:201], v[22:25]
	v_mfma_f32_16x16x32_bf16 v[18:21], v[154:157], v[194:197], v[18:21]
	v_mfma_f32_16x16x32_bf16 v[18:21], v[158:161], v[198:201], v[18:21]
	v_mfma_f32_16x16x32_bf16 v[6:9], v[146:149], v[202:205], v[6:9]
	v_mfma_f32_16x16x32_bf16 v[6:9], v[150:153], v[206:209], v[6:9]
	v_mfma_f32_16x16x32_bf16 v[2:5], v[154:157], v[202:205], v[2:5]
	v_mfma_f32_16x16x32_bf16 v[2:5], v[158:161], v[206:209], v[2:5]
	s_barrier
	s_add_i32 s73, s73, 2
	s_add_u32 s38, s38, 0x100
	s_addc_u32 s39, s39, 0
	s_add_u32 s71, s71, 0x100
	s_addc_u32 s72, s72, 0
	s_cmp_gt_u32 s73, 61

.LBB0_2055:
	s_ashr_i32 s31, s30, 31
	s_lshl_b64 s[18:19], s[30:31], 20
	s_add_u32 s34, s27, s18
	s_addc_u32 s35, s44, s19
	s_and_b64 s[18:19], s[0:1], exec
	s_cselect_b32 s31, s35, s3
	s_cselect_b32 s87, s34, s2
	s_ashr_i32 s29, s28, 31
	s_lshl_b64 s[18:19], s[28:29], 20
	s_add_u32 s36, s45, s18
	s_addc_u32 s37, s46, s19
	s_and_b64 s[18:19], s[0:1], exec
	s_cselect_b32 s29, s37, s5
	s_cselect_b32 s90, s36, s4
	s_add_u32 s91, s4, 0x100
	s_addc_u32 s92, s5, 0
	s_mov_b32 s93, -2
	ds_read_b128 v[130:133], v234
	ds_read_b128 v[134:137], v234 offset:1024
	ds_read_b128 v[162:165], v234 offset:2048
	ds_read_b128 v[166:169], v234 offset:3072
	ds_read_b128 v[170:173], v235
	ds_read_b128 v[174:177], v235 offset:1024
	ds_read_b128 v[178:181], v235 offset:2048
	ds_read_b128 v[182:185], v235 offset:3072
	s_add_u32 s4, s2, 0x100
	s_addc_u32 s5, s3, 0
	s_cmp_eq_u32 s93, 28
	s_cselect_b32 s43, s31, s5
	s_cselect_b32 s42, s87, s4
	s_cselect_b32 s19, s29, s92
	s_cselect_b32 s18, s90, s91
	v_lshl_add_u64 v[218:219], s[2:3], 0, v[154:155]
	s_add_i32 m0, s49, 0xc000
	ds_read_b128 v[186:189], v236
	ds_read_b128 v[190:193], v236 offset:1024
	ds_read_b128 v[194:197], v236 offset:2048
	ds_read_b128 v[198:201], v236 offset:3072
	ds_read_b128 v[202:205], v236 offset:4096
	ds_read_b128 v[206:209], v236 offset:5120
	ds_read_b128 v[210:213], v236 offset:6144
	ds_read_b128 v[214:217], v236 offset:7168
	global_load_lds_dwordx4 v[218:219], off
	v_lshl_add_u64 v[218:219], s[2:3], 0, v[156:157]
	s_add_i32 m0, s49, 0xe000
	s_nop 0
	global_load_lds_dwordx4 v[218:219], off
	s_waitcnt vmcnt(24)
	s_cmp_lg_u32 s41, 0
	s_cbranch_scc1 .Lrlx6_0
	s_waitcnt vmcnt(8)
.Lrlx6_0:
	s_waitcnt lgkmcnt(0)
	s_barrier
	s_waitcnt lgkmcnt(0)
	v_mfma_i32_16x16x64_i8 v[118:121], v[130:133], v[186:189], 0
	v_mfma_i32_16x16x64_i8 v[118:121], v[134:137], v[190:193], v[118:121]
	v_mfma_i32_16x16x64_i8 v[102:105], v[162:165], v[186:189], 0
	v_mfma_i32_16x16x64_i8 v[102:105], v[166:169], v[190:193], v[102:105]
	v_mfma_i32_16x16x64_i8 v[114:117], v[130:133], v[194:197], 0
	v_mfma_i32_16x16x64_i8 v[114:117], v[134:137], v[198:201], v[114:117]
	v_mfma_i32_16x16x64_i8 v[98:101], v[162:165], v[194:197], 0
	v_mfma_i32_16x16x64_i8 v[98:101], v[166:169], v[198:201], v[98:101]
	v_mfma_i32_16x16x64_i8 v[126:129], v[130:133], v[202:205], 0
	v_mfma_i32_16x16x64_i8 v[126:129], v[134:137], v[206:209], v[126:129]
	v_mfma_i32_16x16x64_i8 v[110:113], v[162:165], v[202:205], 0
	v_mfma_i32_16x16x64_i8 v[110:113], v[166:169], v[206:209], v[110:113]
	v_mfma_i32_16x16x64_i8 v[122:125], v[130:133], v[210:213], 0
	v_mfma_i32_16x16x64_i8 v[122:125], v[134:137], v[214:217], v[122:125]
	v_mfma_i32_16x16x64_i8 v[106:109], v[162:165], v[210:213], 0
	v_mfma_i32_16x16x64_i8 v[106:109], v[166:169], v[214:217], v[106:109]
	v_mfma_i32_16x16x64_i8 v[86:89], v[170:173], v[186:189], 0
	v_mfma_i32_16x16x64_i8 v[86:89], v[174:177], v[190:193], v[86:89]
	v_mfma_i32_16x16x64_i8 v[70:73], v[178:181], v[186:189], 0
	v_mfma_i32_16x16x64_i8 v[70:73], v[182:185], v[190:193], v[70:73]
	v_mfma_i32_16x16x64_i8 v[82:85], v[170:173], v[194:197], 0
	v_mfma_i32_16x16x64_i8 v[82:85], v[174:177], v[198:201], v[82:85]
	v_mfma_i32_16x16x64_i8 v[66:69], v[178:181], v[194:197], 0
	v_mfma_i32_16x16x64_i8 v[66:69], v[182:185], v[198:201], v[66:69]
	v_mfma_i32_16x16x64_i8 v[94:97], v[170:173], v[202:205], 0
	v_mfma_i32_16x16x64_i8 v[94:97], v[174:177], v[206:209], v[94:97]
	v_mfma_i32_16x16x64_i8 v[78:81], v[178:181], v[202:205], 0
	v_mfma_i32_16x16x64_i8 v[78:81], v[182:185], v[206:209], v[78:81]
	v_mfma_i32_16x16x64_i8 v[90:93], v[170:173], v[210:213], 0
	v_mfma_i32_16x16x64_i8 v[90:93], v[174:177], v[214:217], v[90:93]
	v_mfma_i32_16x16x64_i8 v[74:77], v[178:181], v[210:213], 0
	v_mfma_i32_16x16x64_i8 v[74:77], v[182:185], v[214:217], v[74:77]
	s_barrier
	s_add_i32 s2, s82, s47
	v_lshl_add_u64 v[218:219], s[18:19], 0, v[144:145]
	s_mov_b32 m0, s2
	ds_read_b128 v[186:189], v236 offset:16384
	ds_read_b128 v[190:193], v236 offset:17408
	ds_read_b128 v[194:197], v236 offset:18432
	ds_read_b128 v[198:201], v236 offset:19456
	ds_read_b128 v[202:205], v236 offset:20480
	ds_read_b128 v[206:209], v236 offset:21504
	ds_read_b128 v[210:213], v236 offset:22528
	ds_read_b128 v[214:217], v236 offset:23552
	global_load_lds_dwordx4 v[218:219], off
	s_add_i32 m0, s2, 0x2000
	s_add_u32 s2, s18, 0x80000
	v_lshl_add_u64 v[220:221], s[18:19], 0, v[148:149]
	s_addc_u32 s3, s19, 0
	s_add_i32 s94, s16, s47
	global_load_lds_dwordx4 v[220:221], off
	v_lshl_add_u64 v[222:223], s[2:3], 0, v[144:145]
	s_mov_b32 m0, s94
	v_lshl_add_u64 v[224:225], s[42:43], 0, v[146:147]
	global_load_lds_dwordx4 v[222:223], off
	v_lshl_add_u64 v[222:223], s[2:3], 0, v[148:149]
	s_add_i32 m0, s94, 0x2000
	s_nop 0
	global_load_lds_dwordx4 v[222:223], off
	v_lshl_add_u64 v[222:223], s[42:43], 0, v[142:143]
	s_mov_b32 m0, s49
	s_nop 0
	global_load_lds_dwordx4 v[222:223], off
	s_mov_b32 m0, s50
	s_nop 0
	global_load_lds_dwordx4 v[224:225], off
	s_waitcnt vmcnt(24)
	s_cmp_lg_u32 s41, 0
	s_cbranch_scc1 .Lrlx6_1
	s_waitcnt vmcnt(8)
.Lrlx6_1:
	s_waitcnt lgkmcnt(0)
	s_barrier
	s_waitcnt lgkmcnt(0)
	v_mfma_i32_16x16x64_i8 v[54:57], v[130:133], v[186:189], 0
	v_mfma_i32_16x16x64_i8 v[54:57], v[134:137], v[190:193], v[54:57]
	v_mfma_i32_16x16x64_i8 v[18:21], v[162:165], v[186:189], 0
	v_mfma_i32_16x16x64_i8 v[18:21], v[166:169], v[190:193], v[18:21]
	v_mfma_i32_16x16x64_i8 v[50:53], v[130:133], v[194:197], 0
	v_mfma_i32_16x16x64_i8 v[50:53], v[134:137], v[198:201], v[50:53]
	v_mfma_i32_16x16x64_i8 v[22:25], v[162:165], v[194:197], 0
	v_mfma_i32_16x16x64_i8 v[22:25], v[166:169], v[198:201], v[22:25]
	v_mfma_i32_16x16x64_i8 v[62:65], v[130:133], v[202:205], 0
	v_mfma_i32_16x16x64_i8 v[62:65], v[134:137], v[206:209], v[62:65]
	v_mfma_i32_16x16x64_i8 v[30:33], v[162:165], v[202:205], 0
	v_mfma_i32_16x16x64_i8 v[30:33], v[166:169], v[206:209], v[30:33]
	v_mfma_i32_16x16x64_i8 v[58:61], v[130:133], v[210:213], 0
	v_mfma_i32_16x16x64_i8 v[58:61], v[134:137], v[214:217], v[58:61]
	v_mfma_i32_16x16x64_i8 v[26:29], v[162:165], v[210:213], 0
	v_mfma_i32_16x16x64_i8 v[26:29], v[166:169], v[214:217], v[26:29]
	v_mfma_i32_16x16x64_i8 v[46:49], v[170:173], v[186:189], 0
	v_mfma_i32_16x16x64_i8 v[46:49], v[174:177], v[190:193], v[46:49]
	v_mfma_i32_16x16x64_i8 v[14:17], v[178:181], v[186:189], 0
	v_mfma_i32_16x16x64_i8 v[14:17], v[182:185], v[190:193], v[14:17]
	v_mfma_i32_16x16x64_i8 v[42:45], v[170:173], v[194:197], 0
	v_mfma_i32_16x16x64_i8 v[42:45], v[174:177], v[198:201], v[42:45]
	v_mfma_i32_16x16x64_i8 v[10:13], v[178:181], v[194:197], 0
	v_mfma_i32_16x16x64_i8 v[10:13], v[182:185], v[198:201], v[10:13]
	v_mfma_i32_16x16x64_i8 v[38:41], v[170:173], v[202:205], 0
	v_mfma_i32_16x16x64_i8 v[38:41], v[174:177], v[206:209], v[38:41]
	v_mfma_i32_16x16x64_i8 v[6:9], v[178:181], v[202:205], 0
	v_mfma_i32_16x16x64_i8 v[6:9], v[182:185], v[206:209], v[6:9]
	v_mfma_i32_16x16x64_i8 v[34:37], v[170:173], v[210:213], 0
	v_mfma_i32_16x16x64_i8 v[34:37], v[174:177], v[214:217], v[34:37]
	v_mfma_i32_16x16x64_i8 v[2:5], v[178:181], v[210:213], 0
	v_mfma_i32_16x16x64_i8 v[2:5], v[182:185], v[214:217], v[2:5]
	s_barrier
	s_add_i32 s94, 0, 0x18000
	s_add_i32 s95, 0, 0x1c000
	v_add_u32_e32 v166, s94, v232
	v_add_u32_e32 v182, s95, v232
	ds_read_b128 v[130:133], v166
	ds_read_b128 v[134:137], v166 offset:1024
	ds_read_b128 v[162:165], v166 offset:2048
	ds_read_b128 v[166:169], v166 offset:3072
	ds_read_b128 v[170:173], v182
	ds_read_b128 v[174:177], v182 offset:1024
	ds_read_b128 v[178:181], v182 offset:2048
	ds_read_b128 v[182:185], v182 offset:3072
	s_add_u32 s2, s42, 0x80000
	s_addc_u32 s3, s43, 0
	s_mov_b32 m0, s51
	v_lshl_add_u64 v[226:227], s[2:3], 0, v[142:143]
	ds_read_b128 v[186:189], v236 offset:32768
	ds_read_b128 v[190:193], v236 offset:33792
	ds_read_b128 v[194:197], v236 offset:34816
	ds_read_b128 v[198:201], v236 offset:35840
	ds_read_b128 v[202:205], v236 offset:36864
	ds_read_b128 v[206:209], v236 offset:37888
	ds_read_b128 v[210:213], v236 offset:38912
	ds_read_b128 v[214:217], v236 offset:39936
	global_load_lds_dwordx4 v[226:227], off
	v_lshl_add_u64 v[226:227], s[2:3], 0, v[146:147]
	s_mov_b32 m0, s54
	s_nop 0
	global_load_lds_dwordx4 v[226:227], off
	s_waitcnt vmcnt(8)
	s_waitcnt lgkmcnt(0)
	s_barrier
	s_waitcnt lgkmcnt(0)
	v_mfma_i32_16x16x64_i8 v[118:121], v[130:133], v[186:189], v[118:121]
	v_mfma_i32_16x16x64_i8 v[118:121], v[134:137], v[190:193], v[118:121]
	v_mfma_i32_16x16x64_i8 v[102:105], v[162:165], v[186:189], v[102:105]
	v_mfma_i32_16x16x64_i8 v[102:105], v[166:169], v[190:193], v[102:105]
	v_mfma_i32_16x16x64_i8 v[114:117], v[130:133], v[194:197], v[114:117]
	v_mfma_i32_16x16x64_i8 v[114:117], v[134:137], v[198:201], v[114:117]
	v_mfma_i32_16x16x64_i8 v[98:101], v[162:165], v[194:197], v[98:101]
	v_mfma_i32_16x16x64_i8 v[98:101], v[166:169], v[198:201], v[98:101]
	v_mfma_i32_16x16x64_i8 v[126:129], v[130:133], v[202:205], v[126:129]
	v_mfma_i32_16x16x64_i8 v[126:129], v[134:137], v[206:209], v[126:129]
	v_mfma_i32_16x16x64_i8 v[110:113], v[162:165], v[202:205], v[110:113]
	v_mfma_i32_16x16x64_i8 v[110:113], v[166:169], v[206:209], v[110:113]
	v_mfma_i32_16x16x64_i8 v[122:125], v[130:133], v[210:213], v[122:125]
	v_mfma_i32_16x16x64_i8 v[122:125], v[134:137], v[214:217], v[122:125]
	v_mfma_i32_16x16x64_i8 v[106:109], v[162:165], v[210:213], v[106:109]
	v_mfma_i32_16x16x64_i8 v[106:109], v[166:169], v[214:217], v[106:109]
	v_mfma_i32_16x16x64_i8 v[86:89], v[170:173], v[186:189], v[86:89]
	v_mfma_i32_16x16x64_i8 v[86:89], v[174:177], v[190:193], v[86:89]
	v_mfma_i32_16x16x64_i8 v[70:73], v[178:181], v[186:189], v[70:73]
	v_mfma_i32_16x16x64_i8 v[70:73], v[182:185], v[190:193], v[70:73]
	v_mfma_i32_16x16x64_i8 v[82:85], v[170:173], v[194:197], v[82:85]
	v_mfma_i32_16x16x64_i8 v[82:85], v[174:177], v[198:201], v[82:85]
	v_mfma_i32_16x16x64_i8 v[66:69], v[178:181], v[194:197], v[66:69]
	v_mfma_i32_16x16x64_i8 v[66:69], v[182:185], v[198:201], v[66:69]
	v_mfma_i32_16x16x64_i8 v[94:97], v[170:173], v[202:205], v[94:97]
	v_mfma_i32_16x16x64_i8 v[94:97], v[174:177], v[206:209], v[94:97]
	v_mfma_i32_16x16x64_i8 v[78:81], v[178:181], v[202:205], v[78:81]
	v_mfma_i32_16x16x64_i8 v[78:81], v[182:185], v[206:209], v[78:81]
	v_mfma_i32_16x16x64_i8 v[90:93], v[170:173], v[210:213], v[90:93]
	v_mfma_i32_16x16x64_i8 v[90:93], v[174:177], v[214:217], v[90:93]
	v_mfma_i32_16x16x64_i8 v[74:77], v[178:181], v[210:213], v[74:77]
	v_mfma_i32_16x16x64_i8 v[74:77], v[182:185], v[214:217], v[74:77]
	s_barrier
	s_add_i32 s2, s94, s47
	v_lshl_add_u64 v[218:219], v[218:219], 0, s[14:15]
	s_mov_b32 m0, s2
	ds_read_b128 v[186:189], v236 offset:49152
	ds_read_b128 v[190:193], v236 offset:50176
	ds_read_b128 v[194:197], v236 offset:51200
	ds_read_b128 v[198:201], v236 offset:52224
	ds_read_b128 v[202:205], v236 offset:53248
	ds_read_b128 v[206:209], v236 offset:54272
	ds_read_b128 v[210:213], v236 offset:55296
	ds_read_b128 v[214:217], v236 offset:56320
	global_load_lds_dwordx4 v[218:219], off
	s_add_i32 m0, s2, 0x2000
	s_add_u32 s2, s18, 0x80080
	v_lshl_add_u64 v[218:219], v[220:221], 0, s[14:15]
	s_addc_u32 s3, s19, 0
	s_add_i32 s18, s95, s47
	global_load_lds_dwordx4 v[218:219], off
	v_lshl_add_u64 v[218:219], s[2:3], 0, v[144:145]
	s_mov_b32 m0, s18
	s_nop 0
	global_load_lds_dwordx4 v[218:219], off
	v_lshl_add_u64 v[218:219], s[2:3], 0, v[148:149]
	s_add_i32 m0, s18, 0x2000
	s_nop 0
	global_load_lds_dwordx4 v[218:219], off
	v_lshl_add_u64 v[218:219], v[222:223], 0, s[14:15]
	s_mov_b32 m0, s63
	s_nop 0
	global_load_lds_dwordx4 v[218:219], off
	v_lshl_add_u64 v[218:219], v[224:225], 0, s[14:15]
	s_mov_b32 m0, s64
	s_nop 0
	global_load_lds_dwordx4 v[218:219], off
	s_waitcnt vmcnt(8)
	s_waitcnt lgkmcnt(0)
	s_barrier
	s_waitcnt lgkmcnt(0)
	v_mfma_i32_16x16x64_i8 v[54:57], v[130:133], v[186:189], v[54:57]
	v_mfma_i32_16x16x64_i8 v[54:57], v[134:137], v[190:193], v[54:57]
	v_mfma_i32_16x16x64_i8 v[18:21], v[162:165], v[186:189], v[18:21]
	v_mfma_i32_16x16x64_i8 v[18:21], v[166:169], v[190:193], v[18:21]
	v_mfma_i32_16x16x64_i8 v[50:53], v[130:133], v[194:197], v[50:53]
	v_mfma_i32_16x16x64_i8 v[50:53], v[134:137], v[198:201], v[50:53]
	v_mfma_i32_16x16x64_i8 v[22:25], v[162:165], v[194:197], v[22:25]
	v_mfma_i32_16x16x64_i8 v[22:25], v[166:169], v[198:201], v[22:25]
	v_mfma_i32_16x16x64_i8 v[62:65], v[130:133], v[202:205], v[62:65]
	v_mfma_i32_16x16x64_i8 v[62:65], v[134:137], v[206:209], v[62:65]
	v_mfma_i32_16x16x64_i8 v[30:33], v[162:165], v[202:205], v[30:33]
	v_mfma_i32_16x16x64_i8 v[30:33], v[166:169], v[206:209], v[30:33]
	v_mfma_i32_16x16x64_i8 v[58:61], v[130:133], v[210:213], v[58:61]
	v_mfma_i32_16x16x64_i8 v[58:61], v[134:137], v[214:217], v[58:61]
	v_mfma_i32_16x16x64_i8 v[26:29], v[162:165], v[210:213], v[26:29]
	v_mfma_i32_16x16x64_i8 v[26:29], v[166:169], v[214:217], v[26:29]
	v_mfma_i32_16x16x64_i8 v[46:49], v[170:173], v[186:189], v[46:49]
	v_mfma_i32_16x16x64_i8 v[46:49], v[174:177], v[190:193], v[46:49]
	v_mfma_i32_16x16x64_i8 v[14:17], v[178:181], v[186:189], v[14:17]
	v_mfma_i32_16x16x64_i8 v[14:17], v[182:185], v[190:193], v[14:17]
	v_mfma_i32_16x16x64_i8 v[42:45], v[170:173], v[194:197], v[42:45]
	v_mfma_i32_16x16x64_i8 v[42:45], v[174:177], v[198:201], v[42:45]
	v_mfma_i32_16x16x64_i8 v[10:13], v[178:181], v[194:197], v[10:13]
	v_mfma_i32_16x16x64_i8 v[10:13], v[182:185], v[198:201], v[10:13]
	v_mfma_i32_16x16x64_i8 v[38:41], v[170:173], v[202:205], v[38:41]
	v_mfma_i32_16x16x64_i8 v[38:41], v[174:177], v[206:209], v[38:41]
	v_mfma_i32_16x16x64_i8 v[6:9], v[178:181], v[202:205], v[6:9]
	v_mfma_i32_16x16x64_i8 v[6:9], v[182:185], v[206:209], v[6:9]
	v_mfma_i32_16x16x64_i8 v[34:37], v[170:173], v[210:213], v[34:37]
	v_mfma_i32_16x16x64_i8 v[34:37], v[174:177], v[214:217], v[34:37]
	v_mfma_i32_16x16x64_i8 v[2:5], v[178:181], v[210:213], v[2:5]
	v_mfma_i32_16x16x64_i8 v[2:5], v[182:185], v[214:217], v[2:5]
	s_barrier
	s_add_i32 s93, s93, 2
	s_add_u32 s91, s91, 0x100
	s_addc_u32 s92, s92, 0
	s_cmp_gt_u32 s93, 29
	s_mov_b64 s[2:3], s[4:5]

.LBB0_2240:
	s_add_u32 s69, s36, 0x100
	s_addc_u32 s70, s37, 0
	s_mov_b32 s71, -2
	ds_read_b128 v[130:133], v212
	ds_read_b128 v[134:137], v212 offset:1024
	ds_read_b128 v[138:141], v212 offset:2048
	ds_read_b128 v[142:145], v212 offset:3072
	ds_read_b128 v[146:149], v213
	ds_read_b128 v[150:153], v213 offset:1024
	ds_read_b128 v[154:157], v213 offset:2048
	ds_read_b128 v[158:161], v213 offset:3072
	s_add_u32 s36, s18, 0x100
	s_addc_u32 s37, s19, 0
	s_cmpk_eq_i32 s71, 0xdc
	s_cselect_b32 s41, s3, s37
	s_cselect_b32 s40, s2, s36
	s_cselect_b32 s39, s35, s70
	s_cselect_b32 s38, s34, s69
	v_lshl_add_u64 v[216:217], s[18:19], 0, v[178:179]
	s_add_i32 m0, s44, 0xc000
	ds_read_b128 v[162:165], v214
	ds_read_b128 v[166:169], v214 offset:1024
	ds_read_b128 v[186:189], v214 offset:2048
	ds_read_b128 v[190:193], v214 offset:3072
	ds_read_b128 v[194:197], v214 offset:4096
	ds_read_b128 v[198:201], v214 offset:5120
	ds_read_b128 v[202:205], v214 offset:6144
	ds_read_b128 v[206:209], v214 offset:7168
	global_load_lds_dwordx4 v[216:217], off
	v_lshl_add_u64 v[216:217], s[18:19], 0, v[180:181]
	s_add_i32 m0, s44, 0xe000
	s_nop 0
	global_load_lds_dwordx4 v[216:217], off
	s_waitcnt vmcnt(24)
	s_cmp_lg_u32 s48, 1
	s_cbranch_scc1 .Lrlx7_0
	s_waitcnt vmcnt(8)
.Lrlx7_0:
	s_waitcnt lgkmcnt(0)
	s_barrier
	s_waitcnt lgkmcnt(0)
	v_mfma_f32_16x16x32_bf16 v[126:129], v[130:133], v[162:165], 0
	v_mfma_f32_16x16x32_bf16 v[126:129], v[134:137], v[166:169], v[126:129]
	v_mfma_f32_16x16x32_bf16 v[122:125], v[138:141], v[162:165], 0
	v_mfma_f32_16x16x32_bf16 v[122:125], v[142:145], v[166:169], v[122:125]
	v_mfma_f32_16x16x32_bf16 v[110:113], v[130:133], v[186:189], 0
	v_mfma_f32_16x16x32_bf16 v[110:113], v[134:137], v[190:193], v[110:113]
	v_mfma_f32_16x16x32_bf16 v[106:109], v[138:141], v[186:189], 0
	v_mfma_f32_16x16x32_bf16 v[106:109], v[142:145], v[190:193], v[106:109]
	v_mfma_f32_16x16x32_bf16 v[94:97], v[130:133], v[194:197], 0
	v_mfma_f32_16x16x32_bf16 v[94:97], v[134:137], v[198:201], v[94:97]
	v_mfma_f32_16x16x32_bf16 v[90:93], v[138:141], v[194:197], 0
	v_mfma_f32_16x16x32_bf16 v[90:93], v[142:145], v[198:201], v[90:93]
	v_mfma_f32_16x16x32_bf16 v[78:81], v[130:133], v[202:205], 0
	v_mfma_f32_16x16x32_bf16 v[78:81], v[134:137], v[206:209], v[78:81]
	v_mfma_f32_16x16x32_bf16 v[74:77], v[138:141], v[202:205], 0
	v_mfma_f32_16x16x32_bf16 v[74:77], v[142:145], v[206:209], v[74:77]
	v_mfma_f32_16x16x32_bf16 v[118:121], v[146:149], v[162:165], 0
	v_mfma_f32_16x16x32_bf16 v[118:121], v[150:153], v[166:169], v[118:121]
	v_mfma_f32_16x16x32_bf16 v[114:117], v[154:157], v[162:165], 0
	v_mfma_f32_16x16x32_bf16 v[114:117], v[158:161], v[166:169], v[114:117]
	v_mfma_f32_16x16x32_bf16 v[102:105], v[146:149], v[186:189], 0
	v_mfma_f32_16x16x32_bf16 v[102:105], v[150:153], v[190:193], v[102:105]
	v_mfma_f32_16x16x32_bf16 v[98:101], v[154:157], v[186:189], 0
	v_mfma_f32_16x16x32_bf16 v[98:101], v[158:161], v[190:193], v[98:101]
	v_mfma_f32_16x16x32_bf16 v[86:89], v[146:149], v[194:197], 0
	v_mfma_f32_16x16x32_bf16 v[86:89], v[150:153], v[198:201], v[86:89]
	v_mfma_f32_16x16x32_bf16 v[82:85], v[154:157], v[194:197], 0
	v_mfma_f32_16x16x32_bf16 v[82:85], v[158:161], v[198:201], v[82:85]
	v_mfma_f32_16x16x32_bf16 v[70:73], v[146:149], v[202:205], 0
	v_mfma_f32_16x16x32_bf16 v[70:73], v[150:153], v[206:209], v[70:73]
	v_mfma_f32_16x16x32_bf16 v[66:69], v[154:157], v[202:205], 0
	v_mfma_f32_16x16x32_bf16 v[66:69], v[158:161], v[206:209], v[66:69]
	s_barrier
	s_add_i32 s18, s56, s43
	v_lshl_add_u64 v[216:217], s[38:39], 0, v[172:173]
	s_mov_b32 m0, s18
	ds_read_b128 v[162:165], v214 offset:16384
	ds_read_b128 v[166:169], v214 offset:17408
	ds_read_b128 v[186:189], v214 offset:18432
	ds_read_b128 v[190:193], v214 offset:19456
	ds_read_b128 v[194:197], v214 offset:20480
	ds_read_b128 v[198:201], v214 offset:21504
	ds_read_b128 v[202:205], v214 offset:22528
	ds_read_b128 v[206:209], v214 offset:23552
	global_load_lds_dwordx4 v[216:217], off
	s_add_i32 m0, s18, 0x2000
	s_add_u32 s18, s38, 0x380000
	v_lshl_add_u64 v[218:219], s[38:39], 0, v[176:177]
	s_addc_u32 s19, s39, 0
	s_add_i32 s72, s57, s43
	global_load_lds_dwordx4 v[218:219], off
	v_lshl_add_u64 v[220:221], s[18:19], 0, v[172:173]
	s_mov_b32 m0, s72
	v_lshl_add_u64 v[222:223], s[40:41], 0, v[174:175]
	global_load_lds_dwordx4 v[220:221], off
	v_lshl_add_u64 v[220:221], s[18:19], 0, v[176:177]
	s_add_i32 m0, s72, 0x2000
	s_nop 0
	global_load_lds_dwordx4 v[220:221], off
	v_lshl_add_u64 v[220:221], s[40:41], 0, v[170:171]
	s_mov_b32 m0, s44
	s_nop 0
	global_load_lds_dwordx4 v[220:221], off
	s_mov_b32 m0, s45
	s_nop 0
	global_load_lds_dwordx4 v[222:223], off
	s_waitcnt vmcnt(24)
	s_cmp_lg_u32 s48, 1
	s_cbranch_scc1 .Lrlx7_1
	s_waitcnt vmcnt(8)
.Lrlx7_1:
	s_waitcnt lgkmcnt(0)
	s_barrier
	s_waitcnt lgkmcnt(0)
	v_mfma_f32_16x16x32_bf16 v[62:65], v[130:133], v[162:165], 0
	v_mfma_f32_16x16x32_bf16 v[62:65], v[134:137], v[166:169], v[62:65]
	v_mfma_f32_16x16x32_bf16 v[58:61], v[138:141], v[162:165], 0
	v_mfma_f32_16x16x32_bf16 v[58:61], v[142:145], v[166:169], v[58:61]
	v_mfma_f32_16x16x32_bf16 v[46:49], v[130:133], v[186:189], 0
	v_mfma_f32_16x16x32_bf16 v[46:49], v[134:137], v[190:193], v[46:49]
	v_mfma_f32_16x16x32_bf16 v[42:45], v[138:141], v[186:189], 0
	v_mfma_f32_16x16x32_bf16 v[42:45], v[142:145], v[190:193], v[42:45]
	v_mfma_f32_16x16x32_bf16 v[30:33], v[130:133], v[194:197], 0
	v_mfma_f32_16x16x32_bf16 v[30:33], v[134:137], v[198:201], v[30:33]
	v_mfma_f32_16x16x32_bf16 v[26:29], v[138:141], v[194:197], 0
	v_mfma_f32_16x16x32_bf16 v[26:29], v[142:145], v[198:201], v[26:29]
	v_mfma_f32_16x16x32_bf16 v[14:17], v[130:133], v[202:205], 0
	v_mfma_f32_16x16x32_bf16 v[14:17], v[134:137], v[206:209], v[14:17]
	v_mfma_f32_16x16x32_bf16 v[10:13], v[138:141], v[202:205], 0
	v_mfma_f32_16x16x32_bf16 v[10:13], v[142:145], v[206:209], v[10:13]
	v_mfma_f32_16x16x32_bf16 v[54:57], v[146:149], v[162:165], 0
	v_mfma_f32_16x16x32_bf16 v[54:57], v[150:153], v[166:169], v[54:57]
	v_mfma_f32_16x16x32_bf16 v[50:53], v[154:157], v[162:165], 0
	v_mfma_f32_16x16x32_bf16 v[50:53], v[158:161], v[166:169], v[50:53]
	v_mfma_f32_16x16x32_bf16 v[38:41], v[146:149], v[186:189], 0
	v_mfma_f32_16x16x32_bf16 v[38:41], v[150:153], v[190:193], v[38:41]
	v_mfma_f32_16x16x32_bf16 v[34:37], v[154:157], v[186:189], 0
	v_mfma_f32_16x16x32_bf16 v[34:37], v[158:161], v[190:193], v[34:37]
	v_mfma_f32_16x16x32_bf16 v[22:25], v[146:149], v[194:197], 0
	v_mfma_f32_16x16x32_bf16 v[22:25], v[150:153], v[198:201], v[22:25]
	v_mfma_f32_16x16x32_bf16 v[18:21], v[154:157], v[194:197], 0
	v_mfma_f32_16x16x32_bf16 v[18:21], v[158:161], v[198:201], v[18:21]
	v_mfma_f32_16x16x32_bf16 v[6:9], v[146:149], v[202:205], 0
	v_mfma_f32_16x16x32_bf16 v[6:9], v[150:153], v[206:209], v[6:9]
	v_mfma_f32_16x16x32_bf16 v[2:5], v[154:157], v[202:205], 0
	v_mfma_f32_16x16x32_bf16 v[2:5], v[158:161], v[206:209], v[2:5]
	s_barrier
	s_add_i32 s72, 0, 0x18000
	s_add_i32 s73, 0, 0x1c000
	v_add_u32_e32 v142, s72, v211
	v_add_u32_e32 v158, s73, v211
	ds_read_b128 v[130:133], v142
	ds_read_b128 v[134:137], v142 offset:1024
	ds_read_b128 v[138:141], v142 offset:2048
	ds_read_b128 v[142:145], v142 offset:3072
	ds_read_b128 v[146:149], v158
	ds_read_b128 v[150:153], v158 offset:1024
	ds_read_b128 v[154:157], v158 offset:2048
	ds_read_b128 v[158:161], v158 offset:3072
	s_add_u32 s18, s40, 0x380000
	s_addc_u32 s19, s41, 0
	s_mov_b32 m0, s46
	v_lshl_add_u64 v[224:225], s[18:19], 0, v[170:171]
	ds_read_b128 v[162:165], v214 offset:32768
	ds_read_b128 v[166:169], v214 offset:33792
	ds_read_b128 v[186:189], v214 offset:34816
	ds_read_b128 v[190:193], v214 offset:35840
	ds_read_b128 v[194:197], v214 offset:36864
	ds_read_b128 v[198:201], v214 offset:37888
	ds_read_b128 v[202:205], v214 offset:38912
	ds_read_b128 v[206:209], v214 offset:39936
	global_load_lds_dwordx4 v[224:225], off
	v_lshl_add_u64 v[224:225], s[18:19], 0, v[174:175]
	s_mov_b32 m0, s47
	s_nop 0
	global_load_lds_dwordx4 v[224:225], off
	s_waitcnt vmcnt(8)
	s_waitcnt lgkmcnt(0)
	s_barrier
	s_waitcnt lgkmcnt(0)
	v_mfma_f32_16x16x32_bf16 v[126:129], v[130:133], v[162:165], v[126:129]
	v_mfma_f32_16x16x32_bf16 v[126:129], v[134:137], v[166:169], v[126:129]
	v_mfma_f32_16x16x32_bf16 v[122:125], v[138:141], v[162:165], v[122:125]
	v_mfma_f32_16x16x32_bf16 v[122:125], v[142:145], v[166:169], v[122:125]
	v_mfma_f32_16x16x32_bf16 v[110:113], v[130:133], v[186:189], v[110:113]
	v_mfma_f32_16x16x32_bf16 v[110:113], v[134:137], v[190:193], v[110:113]
	v_mfma_f32_16x16x32_bf16 v[106:109], v[138:141], v[186:189], v[106:109]
	v_mfma_f32_16x16x32_bf16 v[106:109], v[142:145], v[190:193], v[106:109]
	v_mfma_f32_16x16x32_bf16 v[94:97], v[130:133], v[194:197], v[94:97]
	v_mfma_f32_16x16x32_bf16 v[94:97], v[134:137], v[198:201], v[94:97]
	v_mfma_f32_16x16x32_bf16 v[90:93], v[138:141], v[194:197], v[90:93]
	v_mfma_f32_16x16x32_bf16 v[90:93], v[142:145], v[198:201], v[90:93]
	v_mfma_f32_16x16x32_bf16 v[78:81], v[130:133], v[202:205], v[78:81]
	v_mfma_f32_16x16x32_bf16 v[78:81], v[134:137], v[206:209], v[78:81]
	v_mfma_f32_16x16x32_bf16 v[74:77], v[138:141], v[202:205], v[74:77]
	v_mfma_f32_16x16x32_bf16 v[74:77], v[142:145], v[206:209], v[74:77]
	v_mfma_f32_16x16x32_bf16 v[118:121], v[146:149], v[162:165], v[118:121]
	v_mfma_f32_16x16x32_bf16 v[118:121], v[150:153], v[166:169], v[118:121]
	v_mfma_f32_16x16x32_bf16 v[114:117], v[154:157], v[162:165], v[114:117]
	v_mfma_f32_16x16x32_bf16 v[114:117], v[158:161], v[166:169], v[114:117]
	v_mfma_f32_16x16x32_bf16 v[102:105], v[146:149], v[186:189], v[102:105]
	v_mfma_f32_16x16x32_bf16 v[102:105], v[150:153], v[190:193], v[102:105]
	v_mfma_f32_16x16x32_bf16 v[98:101], v[154:157], v[186:189], v[98:101]
	v_mfma_f32_16x16x32_bf16 v[98:101], v[158:161], v[190:193], v[98:101]
	v_mfma_f32_16x16x32_bf16 v[86:89], v[146:149], v[194:197], v[86:89]
	v_mfma_f32_16x16x32_bf16 v[86:89], v[150:153], v[198:201], v[86:89]
	v_mfma_f32_16x16x32_bf16 v[82:85], v[154:157], v[194:197], v[82:85]
	v_mfma_f32_16x16x32_bf16 v[82:85], v[158:161], v[198:201], v[82:85]
	v_mfma_f32_16x16x32_bf16 v[70:73], v[146:149], v[202:205], v[70:73]
	v_mfma_f32_16x16x32_bf16 v[70:73], v[150:153], v[206:209], v[70:73]
	v_mfma_f32_16x16x32_bf16 v[66:69], v[154:157], v[202:205], v[66:69]
	v_mfma_f32_16x16x32_bf16 v[66:69], v[158:161], v[206:209], v[66:69]
	s_barrier
	s_add_i32 s18, s72, s43
	v_lshl_add_u64 v[216:217], v[216:217], 0, s[8:9]
	s_mov_b32 m0, s18
	ds_read_b128 v[162:165], v214 offset:49152
	ds_read_b128 v[166:169], v214 offset:50176
	ds_read_b128 v[186:189], v214 offset:51200
	ds_read_b128 v[190:193], v214 offset:52224
	ds_read_b128 v[194:197], v214 offset:53248
	ds_read_b128 v[198:201], v214 offset:54272
	ds_read_b128 v[202:205], v214 offset:55296
	ds_read_b128 v[206:209], v214 offset:56320
	global_load_lds_dwordx4 v[216:217], off
	s_add_i32 m0, s18, 0x2000
	s_add_u32 s18, s38, 0x380080
	v_lshl_add_u64 v[216:217], v[218:219], 0, s[8:9]
	s_addc_u32 s19, s39, 0
	s_add_i32 s38, s73, s43
	global_load_lds_dwordx4 v[216:217], off
	v_lshl_add_u64 v[216:217], s[18:19], 0, v[172:173]
	s_mov_b32 m0, s38
	s_nop 0
	global_load_lds_dwordx4 v[216:217], off
	v_lshl_add_u64 v[216:217], s[18:19], 0, v[176:177]
	s_add_i32 m0, s38, 0x2000
	s_nop 0
	global_load_lds_dwordx4 v[216:217], off
	v_lshl_add_u64 v[216:217], v[220:221], 0, s[8:9]
	s_mov_b32 m0, s51
	s_nop 0
	global_load_lds_dwordx4 v[216:217], off
	v_lshl_add_u64 v[216:217], v[222:223], 0, s[8:9]
	s_mov_b32 m0, s54
	s_nop 0
	global_load_lds_dwordx4 v[216:217], off
	s_waitcnt vmcnt(8)
	s_waitcnt lgkmcnt(0)
	s_barrier
	s_waitcnt lgkmcnt(0)
	v_mfma_f32_16x16x32_bf16 v[62:65], v[130:133], v[162:165], v[62:65]
	v_mfma_f32_16x16x32_bf16 v[62:65], v[134:137], v[166:169], v[62:65]
	v_mfma_f32_16x16x32_bf16 v[58:61], v[138:141], v[162:165], v[58:61]
	v_mfma_f32_16x16x32_bf16 v[58:61], v[142:145], v[166:169], v[58:61]
	v_mfma_f32_16x16x32_bf16 v[46:49], v[130:133], v[186:189], v[46:49]
	v_mfma_f32_16x16x32_bf16 v[46:49], v[134:137], v[190:193], v[46:49]
	v_mfma_f32_16x16x32_bf16 v[42:45], v[138:141], v[186:189], v[42:45]
	v_mfma_f32_16x16x32_bf16 v[42:45], v[142:145], v[190:193], v[42:45]
	v_mfma_f32_16x16x32_bf16 v[30:33], v[130:133], v[194:197], v[30:33]
	v_mfma_f32_16x16x32_bf16 v[30:33], v[134:137], v[198:201], v[30:33]
	v_mfma_f32_16x16x32_bf16 v[26:29], v[138:141], v[194:197], v[26:29]
	v_mfma_f32_16x16x32_bf16 v[26:29], v[142:145], v[198:201], v[26:29]
	v_mfma_f32_16x16x32_bf16 v[14:17], v[130:133], v[202:205], v[14:17]
	v_mfma_f32_16x16x32_bf16 v[14:17], v[134:137], v[206:209], v[14:17]
	v_mfma_f32_16x16x32_bf16 v[10:13], v[138:141], v[202:205], v[10:13]
	v_mfma_f32_16x16x32_bf16 v[10:13], v[142:145], v[206:209], v[10:13]
	v_mfma_f32_16x16x32_bf16 v[54:57], v[146:149], v[162:165], v[54:57]
	v_mfma_f32_16x16x32_bf16 v[54:57], v[150:153], v[166:169], v[54:57]
	v_mfma_f32_16x16x32_bf16 v[50:53], v[154:157], v[162:165], v[50:53]
	v_mfma_f32_16x16x32_bf16 v[50:53], v[158:161], v[166:169], v[50:53]
	v_mfma_f32_16x16x32_bf16 v[38:41], v[146:149], v[186:189], v[38:41]
	v_mfma_f32_16x16x32_bf16 v[38:41], v[150:153], v[190:193], v[38:41]
	v_mfma_f32_16x16x32_bf16 v[34:37], v[154:157], v[186:189], v[34:37]
	v_mfma_f32_16x16x32_bf16 v[34:37], v[158:161], v[190:193], v[34:37]
	v_mfma_f32_16x16x32_bf16 v[22:25], v[146:149], v[194:197], v[22:25]
	v_mfma_f32_16x16x32_bf16 v[22:25], v[150:153], v[198:201], v[22:25]
	v_mfma_f32_16x16x32_bf16 v[18:21], v[154:157], v[194:197], v[18:21]
	v_mfma_f32_16x16x32_bf16 v[18:21], v[158:161], v[198:201], v[18:21]
	v_mfma_f32_16x16x32_bf16 v[6:9], v[146:149], v[202:205], v[6:9]
	v_mfma_f32_16x16x32_bf16 v[6:9], v[150:153], v[206:209], v[6:9]
	v_mfma_f32_16x16x32_bf16 v[2:5], v[154:157], v[202:205], v[2:5]
	v_mfma_f32_16x16x32_bf16 v[2:5], v[158:161], v[206:209], v[2:5]
	s_barrier
	s_add_i32 s71, s71, 2
	s_add_u32 s69, s69, 0x100
	s_addc_u32 s70, s70, 0
	s_cmpk_gt_u32 s71, 0xdd
	s_mov_b64 s[18:19], s[36:37]
